# nt (non-temporal) hint added to once-read streaming loads: P0 absmax passes, both quant_hid_rot passes, final RMSNorm; on top of no-setprio GEMM loops
# speedup vs baseline: 1.0030x; 1.0030x over previous
; __device__ __forceinline__ float bfly16(float x, bool up) { const auto r = __builtin_amdgcn_permlane16_swap(__float_as_uint(x), __float_as_uint(x), false, false); const float a = __uint_as_float(r[0]), b = __uint_as_float(r[1]); return up ? a - b : a + b; }
; __device__ __forceinline__ float bfly32(float x, bool up) { const auto r = __builtin_amdgcn_permlane32_swap(__float_as_uint(x), __float_as_uint(x), false, false); const float a = __uint_as_float(r[0]), b = __uint_as_float(r[1]); return up ? a - b : a + b; }
; template <int ROT>
; __device__ __forceinline__ void gu_absmax(Frame& F, int s_lo, int s_hi) {
;     ...
;         for (int t = 0; t < ntl; ++t) {
;             const float gv = gain ? gain[512 * kb + 64 * t + lane] : 1.0f;
;             f32x4 v[16];
; #pragma unroll
;             for (int i = 0; i < 16; ++i) v[i] = *(const f32x4*)(src + (size_t)(64 * t + 8 * (i >> 1) + (i & 1)) * rowlen);
;             if (ROT) {
; #pragma unroll
;                 for (int st = 1; st <= (ROT <= 3 ? 1 : ROT == 4 ? 2 : 4); st <<= 1)
; #pragma unroll
;                     for (int i = 0; i < 16; ++i) if (!(i & st)) { const f32x4 a = v[i], b = v[i | st]; v[i] = a + b; v[i | st] = a - b; }
;                 { const bool s16 = (lane & 16) != 0, s32 = (lane & 32) != 0;
; #pragma unroll
;                   for (int i = 0; i < 16; ++i)
; #pragma unroll
;                       for (int e = 0; e < 4; ++e) { float x = v[i][e]; if (ROT >= 2) x = bfly16(x, s16); if (ROT >= 3) x = bfly32(x, s32); v[i][e] = x; } }
; #pragma unroll
;                 for (int i = 0; i < 16; ++i) v[i] *= (ROT == 1 ? 0.70710678118654752f : ROT == 2 ? 0.5f : ROT == 3 ? 0.35355339059327373f : ROT == 4 ? 0.25f : 0.17677669529663687f);
;             }
; #pragma unroll
;             for (int i = 0; i < 16; ++i) { const float g = __shfl(gv, 8 * (i >> 1) + 2 * kr + (i & 1)); const f32x4 a = __builtin_elementwise_abs(v[i] * g); cm = __builtin_elementwise_max(cm, a); }
.LBB0_40:
	v_lshl_add_u64 v[38:39], v[6:7], 0, v[2:3]
	v_lshl_add_u64 v[42:43], v[4:5], 0, v[2:3]
	v_lshl_add_u64 v[54:55], v[34:35], 0, v[2:3]
	v_lshl_add_u64 v[56:57], v[32:33], 0, v[2:3]
	v_lshl_add_u64 v[62:63], v[30:31], 0, v[2:3]
	global_load_dwordx4 v[38:41], v[38:39], off nt
	v_lshl_add_u64 v[64:65], v[28:29], 0, v[2:3]
	global_load_dwordx4 v[42:45], v[42:43], off nt
	s_nop 0
	global_load_dwordx4 v[46:49], v[54:55], off nt
	global_load_dwordx4 v[50:53], v[56:57], off nt
	s_nop 0
	global_load_dwordx4 v[54:57], v[62:63], off nt
	global_load_dwordx4 v[58:61], v[64:65], off nt
	v_lshl_add_u64 v[62:63], v[26:27], 0, v[2:3]
	v_lshl_add_u64 v[64:65], v[24:25], 0, v[2:3]
	global_load_dwordx4 v[68:71], v[62:63], off nt
	global_load_dwordx4 v[106:109], v[64:65], off nt
	v_lshl_add_u64 v[62:63], v[22:23], 0, v[2:3]
	v_lshl_add_u64 v[64:65], v[20:21], 0, v[2:3]
	global_load_dwordx4 v[128:131], v[62:63], off nt
	global_load_dwordx4 v[132:135], v[64:65], off nt
	v_lshl_add_u64 v[62:63], v[18:19], 0, v[2:3]
	v_lshl_add_u64 v[64:65], v[16:17], 0, v[2:3]
	global_load_dwordx4 v[136:139], v[62:63], off nt
	global_load_dwordx4 v[140:143], v[64:65], off nt
	v_lshl_add_u64 v[62:63], v[14:15], 0, v[2:3]
	v_lshl_add_u64 v[64:65], v[12:13], 0, v[2:3]
	global_load_dwordx4 v[144:147], v[62:63], off nt
	global_load_dwordx4 v[148:151], v[64:65], off nt
	v_lshl_add_u64 v[62:63], v[10:11], 0, v[2:3]
	v_lshl_add_u64 v[64:65], v[8:9], 0, v[2:3]
	global_load_dwordx4 v[152:155], v[62:63], off nt
	global_load_dwordx4 v[156:159], v[64:65], off nt
	s_add_i32 s24, s24, -1
	v_lshl_add_u64 v[4:5], v[4:5], 0, s[0:1]
	v_lshl_add_u64 v[6:7], v[6:7], 0, s[0:1]
	v_lshl_add_u64 v[8:9], v[8:9], 0, s[0:1]
	v_lshl_add_u64 v[10:11], v[10:11], 0, s[0:1]
	v_lshl_add_u64 v[12:13], v[12:13], 0, s[0:1]
	v_lshl_add_u64 v[14:15], v[14:15], 0, s[0:1]
	v_lshl_add_u64 v[16:17], v[16:17], 0, s[0:1]
	v_lshl_add_u64 v[18:19], v[18:19], 0, s[0:1]
	v_lshl_add_u64 v[20:21], v[20:21], 0, s[0:1]
	v_lshl_add_u64 v[22:23], v[22:23], 0, s[0:1]
	v_lshl_add_u64 v[24:25], v[24:25], 0, s[0:1]
	v_lshl_add_u64 v[26:27], v[26:27], 0, s[0:1]
	v_lshl_add_u64 v[28:29], v[28:29], 0, s[0:1]
	v_lshl_add_u64 v[30:31], v[30:31], 0, s[0:1]
	v_lshl_add_u64 v[32:33], v[32:33], 0, s[0:1]
	v_lshl_add_u64 v[34:35], v[34:35], 0, s[0:1]
	s_cmp_eq_u32 s24, 0
	v_lshl_add_u64 v[36:37], v[36:37], 0, s[14:15]
	s_waitcnt vmcnt(14)
	v_sub_f32_e32 v163, v43, v39
	v_sub_f32_e32 v164, v42, v38
	v_pk_add_f32 v[160:161], v[38:39], v[42:43]
	s_waitcnt vmcnt(12)
	v_sub_f32_e32 v125, v49, v53
	v_sub_f32_e32 v126, v48, v52
	v_sub_f32_e32 v123, v47, v51
	v_sub_f32_e32 v124, v46, v50
	v_pk_add_f32 v[64:65], v[48:49], v[52:53]
	v_pk_add_f32 v[62:63], v[46:47], v[50:51]
	s_waitcnt vmcnt(10)
	v_sub_f32_e32 v121, v57, v61
	v_sub_f32_e32 v122, v56, v60
	v_sub_f32_e32 v119, v55, v59
	v_sub_f32_e32 v120, v54, v58
	v_pk_add_f32 v[60:61], v[56:57], v[60:61]
	v_pk_add_f32 v[58:59], v[54:55], v[58:59]
	s_waitcnt vmcnt(8)
	v_sub_f32_e32 v117, v71, v109
	v_sub_f32_e32 v118, v70, v108
	v_sub_f32_e32 v115, v69, v107
	v_sub_f32_e32 v116, v68, v106
	v_pk_add_f32 v[56:57], v[70:71], v[108:109]
	v_pk_add_f32 v[54:55], v[68:69], v[106:107]
	s_waitcnt vmcnt(6)
	v_sub_f32_e32 v114, v130, v134
	v_sub_f32_e32 v112, v128, v132
	v_pk_add_f32 v[52:53], v[130:131], v[134:135]
	v_pk_add_f32 v[50:51], v[128:129], v[132:133]
	v_mov_b32_e32 v68, v160
	v_mov_b32_e32 v69, v161
	v_mov_b32_e32 v70, v164
	v_mov_b32_e32 v71, v163
	ds_bpermute_b32 v128, v77, v94
	ds_bpermute_b32 v130, v78, v94
	v_permlane16_swap_b32_e32 v160, v68
	v_permlane16_swap_b32_e32 v161, v69
	v_permlane16_swap_b32_e32 v164, v70
	v_permlane16_swap_b32_e32 v163, v71
	v_cndmask_b32_e64 v68, -v68, v68, s[4:5]
	v_cndmask_b32_e64 v69, -v69, v69, s[4:5]
	v_cndmask_b32_e64 v70, -v70, v70, s[4:5]
	v_cndmask_b32_e64 v71, -v71, v71, s[4:5]
	v_add_f32_e32 v68, v68, v160
	v_add_f32_e32 v69, v69, v161
	v_add_f32_e32 v70, v70, v164
	v_add_f32_e32 v71, v71, v163
	v_pk_mul_f32 v[68:69], v[68:69], 0.5 op_sel_hi:[1,0]
	v_pk_mul_f32 v[70:71], v[70:71], 0.5 op_sel_hi:[1,0]
	v_pk_add_f32 v[66:67], v[40:41], v[44:45]
	s_waitcnt lgkmcnt(1)
	v_pk_mul_f32 v[68:69], v[68:69], v[128:129] op_sel_hi:[1,0]
	s_waitcnt lgkmcnt(0)
	v_pk_mul_f32 v[70:71], v[70:71], v[130:131] op_sel_hi:[1,0]
	v_sub_f32_e32 v127, v45, v41
	v_max3_f32 v71, v105, |v69|, |v71|
	v_max3_f32 v103, v103, |v68|, |v70|
	v_mov_b32_e32 v68, v66
	v_mov_b32_e32 v69, v67
	s_nop 0
	v_permlane16_swap_b32_e32 v66, v68
	v_permlane16_swap_b32_e32 v67, v69
	v_sub_f32_e32 v162, v44, v40
	v_cndmask_b32_e64 v68, -v68, v68, s[4:5]
	v_cndmask_b32_e64 v69, -v69, v69, s[4:5]
	v_add_f32_e32 v66, v68, v66
	v_add_f32_e32 v67, v69, v67
	v_mov_b32_e32 v68, v162
	v_mov_b32_e32 v69, v127
	s_nop 0
	v_permlane16_swap_b32_e32 v162, v68
	v_permlane16_swap_b32_e32 v127, v69
	v_cndmask_b32_e64 v68, -v68, v68, s[4:5]
	v_cndmask_b32_e64 v69, -v69, v69, s[4:5]
	v_add_f32_e32 v68, v68, v162
	v_add_f32_e32 v69, v69, v127
	v_pk_mul_f32 v[66:67], v[66:67], 0.5 op_sel_hi:[1,0]
	v_pk_mul_f32 v[68:69], v[68:69], 0.5 op_sel_hi:[1,0]
	v_pk_mul_f32 v[66:67], v[66:67], v[128:129] op_sel_hi:[1,0]
	v_pk_mul_f32 v[68:69], v[68:69], v[130:131] op_sel_hi:[1,0]
	ds_bpermute_b32 v70, v80, v94
	v_max3_f32 v69, v99, |v67|, |v69|
	v_max3_f32 v99, v100, |v66|, |v68|
	v_mov_b32_e32 v66, v64
	v_mov_b32_e32 v67, v65
	s_nop 0
	v_permlane16_swap_b32_e32 v64, v66
	v_permlane16_swap_b32_e32 v65, v67
	v_cndmask_b32_e64 v66, -v66, v66, s[4:5]
	v_cndmask_b32_e64 v67, -v67, v67, s[4:5]
	v_add_f32_e32 v64, v66, v64
	v_add_f32_e32 v65, v67, v65
	v_mov_b32_e32 v66, v126
	v_mov_b32_e32 v67, v125
	ds_bpermute_b32 v68, v79, v94
	v_permlane16_swap_b32_e32 v126, v66
	v_permlane16_swap_b32_e32 v125, v67
	v_cndmask_b32_e64 v66, -v66, v66, s[4:5]
	v_cndmask_b32_e64 v67, -v67, v67, s[4:5]
	v_add_f32_e32 v66, v66, v126
	v_add_f32_e32 v67, v67, v125
	v_pk_mul_f32 v[64:65], v[64:65], 0.5 op_sel_hi:[1,0]
	v_pk_mul_f32 v[66:67], v[66:67], 0.5 op_sel_hi:[1,0]
	s_waitcnt lgkmcnt(0)
; __device__ __forceinline__ float bfly16(float x, bool up) { const auto r = __builtin_amdgcn_permlane16_swap(__float_as_uint(x), __float_as_uint(x), false, false); const float a = __uint_as_float(r[0]), b = __uint_as_float(r[1]); return up ? a - b : a + b; }
; __device__ __forceinline__ float bfly32(float x, bool up) { const auto r = __builtin_amdgcn_permlane32_swap(__float_as_uint(x), __float_as_uint(x), false, false); const float a = __uint_as_float(r[0]), b = __uint_as_float(r[1]); return up ? a - b : a + b; }
; template <int ROT>
; __device__ __forceinline__ void gu_absmax(Frame& F, int s_lo, int s_hi) {
;     ...
;             if (ROT) {
; #pragma unroll
;                 for (int st = 1; st <= (ROT <= 3 ? 1 : ROT == 4 ? 2 : 4); st <<= 1)
; #pragma unroll
;                     for (int i = 0; i < 16; ++i) if (!(i & st)) { const f32x4 a = v[i], b = v[i | st]; v[i] = a + b; v[i | st] = a - b; }
;                 { const bool s16 = (lane & 16) != 0, s32 = (lane & 32) != 0;
; #pragma unroll
;                   for (int i = 0; i < 16; ++i)
; #pragma unroll
;                       for (int e = 0; e < 4; ++e) { float x = v[i][e]; if (ROT >= 2) x = bfly16(x, s16); if (ROT >= 3) x = bfly32(x, s32); v[i][e] = x; } }
; #pragma unroll
;                 for (int i = 0; i < 16; ++i) v[i] *= (ROT == 1 ? 0.70710678118654752f : ROT == 2 ? 0.5f : ROT == 3 ? 0.35355339059327373f : ROT == 4 ? 0.25f : 0.17677669529663687f);
;             }
; #pragma unroll
;             for (int i = 0; i < 16; ++i) { const float g = __shfl(gv, 8 * (i >> 1) + 2 * kr + (i & 1)); const f32x4 a = __builtin_elementwise_abs(v[i] * g); cm = __builtin_elementwise_max(cm, a); }
	v_pk_mul_f32 v[64:65], v[64:65], v[68:69] op_sel_hi:[1,0]
	v_pk_mul_f32 v[66:67], v[66:67], v[70:71] op_sel_hi:[1,0]
	v_sub_f32_e32 v113, v131, v135
	v_max3_f32 v99, v99, |v64|, |v66|
	v_max3_f32 v67, v69, |v65|, |v67|
	v_mov_b32_e32 v64, v62
	v_mov_b32_e32 v65, v63
	s_nop 0
	v_permlane16_swap_b32_e32 v62, v64
	v_permlane16_swap_b32_e32 v63, v65
	v_cndmask_b32_e64 v64, -v64, v64, s[4:5]
	v_cndmask_b32_e64 v65, -v65, v65, s[4:5]
	v_add_f32_e32 v62, v64, v62
	v_add_f32_e32 v63, v65, v63
	v_mov_b32_e32 v64, v124
	v_mov_b32_e32 v65, v123
	s_nop 0
	v_permlane16_swap_b32_e32 v124, v64
	v_permlane16_swap_b32_e32 v123, v65
	v_cndmask_b32_e64 v64, -v64, v64, s[4:5]
	v_cndmask_b32_e64 v65, -v65, v65, s[4:5]
	v_add_f32_e32 v64, v64, v124
	v_add_f32_e32 v65, v65, v123
	v_pk_mul_f32 v[62:63], v[62:63], 0.5 op_sel_hi:[1,0]
	v_pk_mul_f32 v[64:65], v[64:65], 0.5 op_sel_hi:[1,0]
	v_pk_mul_f32 v[62:63], v[62:63], v[68:69] op_sel_hi:[1,0]
	v_pk_mul_f32 v[64:65], v[64:65], v[70:71] op_sel_hi:[1,0]
	ds_bpermute_b32 v66, v82, v94
	v_max3_f32 v68, v103, |v62|, |v64|
	v_max3_f32 v65, v71, |v63|, |v65|
	v_mov_b32_e32 v62, v60
	v_mov_b32_e32 v63, v61
	s_nop 0
	v_permlane16_swap_b32_e32 v60, v62
	v_permlane16_swap_b32_e32 v61, v63
	v_cndmask_b32_e64 v62, -v62, v62, s[4:5]
	v_cndmask_b32_e64 v63, -v63, v63, s[4:5]
	v_add_f32_e32 v60, v62, v60
	v_add_f32_e32 v61, v63, v61
	v_mov_b32_e32 v62, v122
	v_mov_b32_e32 v63, v121
	ds_bpermute_b32 v64, v81, v94
	v_permlane16_swap_b32_e32 v122, v62
	v_permlane16_swap_b32_e32 v121, v63
	v_cndmask_b32_e64 v62, -v62, v62, s[4:5]
	v_cndmask_b32_e64 v63, -v63, v63, s[4:5]
	v_add_f32_e32 v62, v62, v122
	v_add_f32_e32 v63, v63, v121
	v_pk_mul_f32 v[60:61], v[60:61], 0.5 op_sel_hi:[1,0]
	v_pk_mul_f32 v[62:63], v[62:63], 0.5 op_sel_hi:[1,0]
	s_waitcnt lgkmcnt(0)
	v_pk_mul_f32 v[60:61], v[60:61], v[64:65] op_sel_hi:[1,0]
	v_pk_mul_f32 v[62:63], v[62:63], v[66:67] op_sel_hi:[1,0]
	v_sub_f32_e32 v111, v129, v133
	v_max3_f32 v63, v67, |v61|, |v63|
	v_max3_f32 v67, v99, |v60|, |v62|
	v_mov_b32_e32 v60, v58
	v_mov_b32_e32 v61, v59
	s_nop 0
	v_permlane16_swap_b32_e32 v58, v60
	v_permlane16_swap_b32_e32 v59, v61
	v_cndmask_b32_e64 v60, -v60, v60, s[4:5]
	v_cndmask_b32_e64 v61, -v61, v61, s[4:5]
	v_add_f32_e32 v58, v60, v58
	v_add_f32_e32 v59, v61, v59
	v_mov_b32_e32 v60, v120
	v_mov_b32_e32 v61, v119
	s_nop 0
	v_permlane16_swap_b32_e32 v120, v60
	v_permlane16_swap_b32_e32 v119, v61
	v_cndmask_b32_e64 v60, -v60, v60, s[4:5]
	v_cndmask_b32_e64 v61, -v61, v61, s[4:5]
	v_add_f32_e32 v60, v60, v120
	v_add_f32_e32 v61, v61, v119
	v_pk_mul_f32 v[58:59], v[58:59], 0.5 op_sel_hi:[1,0]
	v_pk_mul_f32 v[60:61], v[60:61], 0.5 op_sel_hi:[1,0]
	v_pk_mul_f32 v[58:59], v[58:59], v[64:65] op_sel_hi:[1,0]
	v_pk_mul_f32 v[60:61], v[60:61], v[66:67] op_sel_hi:[1,0]
	ds_bpermute_b32 v62, v84, v94
	v_max3_f32 v61, v65, |v59|, |v61|
	v_max3_f32 v64, v68, |v58|, |v60|
	v_mov_b32_e32 v58, v56
	v_mov_b32_e32 v59, v57
	s_nop 0
	v_permlane16_swap_b32_e32 v56, v58
	v_permlane16_swap_b32_e32 v57, v59
	v_cndmask_b32_e64 v58, -v58, v58, s[4:5]
	v_cndmask_b32_e64 v59, -v59, v59, s[4:5]
	v_add_f32_e32 v56, v58, v56
	v_add_f32_e32 v57, v59, v57
	v_mov_b32_e32 v58, v118
	v_mov_b32_e32 v59, v117
	ds_bpermute_b32 v60, v83, v94
	v_permlane16_swap_b32_e32 v118, v58
	v_permlane16_swap_b32_e32 v117, v59
	v_cndmask_b32_e64 v58, -v58, v58, s[4:5]
	v_cndmask_b32_e64 v59, -v59, v59, s[4:5]
	v_add_f32_e32 v58, v58, v118
	v_add_f32_e32 v59, v59, v117
	v_pk_mul_f32 v[56:57], v[56:57], 0.5 op_sel_hi:[1,0]
	v_pk_mul_f32 v[58:59], v[58:59], 0.5 op_sel_hi:[1,0]
	s_waitcnt lgkmcnt(0)
	v_pk_mul_f32 v[56:57], v[56:57], v[60:61] op_sel_hi:[1,0]
	v_pk_mul_f32 v[58:59], v[58:59], v[62:63] op_sel_hi:[1,0]
	s_waitcnt vmcnt(4)
	v_pk_add_f32 v[48:49], v[138:139], v[142:143]
	v_max3_f32 v65, v67, |v56|, |v58|
	v_max3_f32 v59, v63, |v57|, |v59|
	v_mov_b32_e32 v56, v54
	v_mov_b32_e32 v57, v55
	s_nop 0
	v_permlane16_swap_b32_e32 v54, v56
	v_permlane16_swap_b32_e32 v55, v57
	v_cndmask_b32_e64 v56, -v56, v56, s[4:5]
	v_cndmask_b32_e64 v57, -v57, v57, s[4:5]
	v_add_f32_e32 v54, v56, v54
	v_add_f32_e32 v55, v57, v55
	v_mov_b32_e32 v56, v116
	v_mov_b32_e32 v57, v115
	s_nop 0
	v_permlane16_swap_b32_e32 v116, v56
	v_permlane16_swap_b32_e32 v115, v57
	v_cndmask_b32_e64 v56, -v56, v56, s[4:5]
	v_cndmask_b32_e64 v57, -v57, v57, s[4:5]
	v_add_f32_e32 v56, v56, v116
	v_add_f32_e32 v57, v57, v115
	v_pk_mul_f32 v[54:55], v[54:55], 0.5 op_sel_hi:[1,0]
	v_pk_mul_f32 v[56:57], v[56:57], 0.5 op_sel_hi:[1,0]
	v_pk_mul_f32 v[54:55], v[54:55], v[60:61] op_sel_hi:[1,0]
	v_pk_mul_f32 v[56:57], v[56:57], v[62:63] op_sel_hi:[1,0]
	ds_bpermute_b32 v58, v86, v94
	v_max3_f32 v60, v64, |v54|, |v56|
	v_max3_f32 v57, v61, |v55|, |v57|
	v_mov_b32_e32 v54, v52
	v_mov_b32_e32 v55, v53
	s_nop 0
	v_permlane16_swap_b32_e32 v52, v54
	v_permlane16_swap_b32_e32 v53, v55
	v_cndmask_b32_e64 v54, -v54, v54, s[4:5]
	v_cndmask_b32_e64 v55, -v55, v55, s[4:5]
	v_add_f32_e32 v52, v54, v52
	v_add_f32_e32 v53, v55, v53
	v_mov_b32_e32 v54, v114
	v_mov_b32_e32 v55, v113
	ds_bpermute_b32 v56, v85, v94
	v_permlane16_swap_b32_e32 v114, v54
	v_permlane16_swap_b32_e32 v113, v55
	v_cndmask_b32_e64 v54, -v54, v54, s[4:5]
	v_cndmask_b32_e64 v55, -v55, v55, s[4:5]
	v_add_f32_e32 v54, v54, v114
	v_add_f32_e32 v55, v55, v113
	v_pk_mul_f32 v[52:53], v[52:53], 0.5 op_sel_hi:[1,0]
	v_pk_mul_f32 v[54:55], v[54:55], 0.5 op_sel_hi:[1,0]
	s_waitcnt lgkmcnt(0)
; __device__ __forceinline__ float bfly16(float x, bool up) { const auto r = __builtin_amdgcn_permlane16_swap(__float_as_uint(x), __float_as_uint(x), false, false); const float a = __uint_as_float(r[0]), b = __uint_as_float(r[1]); return up ? a - b : a + b; }
; __device__ __forceinline__ float bfly32(float x, bool up) { const auto r = __builtin_amdgcn_permlane32_swap(__float_as_uint(x), __float_as_uint(x), false, false); const float a = __uint_as_float(r[0]), b = __uint_as_float(r[1]); return up ? a - b : a + b; }
; template <int ROT>
; __device__ __forceinline__ void gu_absmax(Frame& F, int s_lo, int s_hi) {
;     ...
;             if (ROT) {
; #pragma unroll
;                 for (int st = 1; st <= (ROT <= 3 ? 1 : ROT == 4 ? 2 : 4); st <<= 1)
; #pragma unroll
;                     for (int i = 0; i < 16; ++i) if (!(i & st)) { const f32x4 a = v[i], b = v[i | st]; v[i] = a + b; v[i | st] = a - b; }
;                 { const bool s16 = (lane & 16) != 0, s32 = (lane & 32) != 0;
; #pragma unroll
;                   for (int i = 0; i < 16; ++i)
; #pragma unroll
;                       for (int e = 0; e < 4; ++e) { float x = v[i][e]; if (ROT >= 2) x = bfly16(x, s16); if (ROT >= 3) x = bfly32(x, s32); v[i][e] = x; } }
; #pragma unroll
;                 for (int i = 0; i < 16; ++i) v[i] *= (ROT == 1 ? 0.70710678118654752f : ROT == 2 ? 0.5f : ROT == 3 ? 0.35355339059327373f : ROT == 4 ? 0.25f : 0.17677669529663687f);
;             }
; #pragma unroll
;             for (int i = 0; i < 16; ++i) { const float g = __shfl(gv, 8 * (i >> 1) + 2 * kr + (i & 1)); const f32x4 a = __builtin_elementwise_abs(v[i] * g); cm = __builtin_elementwise_max(cm, a); }
	v_pk_mul_f32 v[52:53], v[52:53], v[56:57] op_sel_hi:[1,0]
	v_pk_mul_f32 v[54:55], v[54:55], v[58:59] op_sel_hi:[1,0]
	v_sub_f32_e32 v109, v139, v143
	v_max3_f32 v55, v59, |v53|, |v55|
	v_max3_f32 v59, v65, |v52|, |v54|
	v_mov_b32_e32 v52, v50
	v_mov_b32_e32 v53, v51
	s_nop 0
	v_permlane16_swap_b32_e32 v50, v52
	v_permlane16_swap_b32_e32 v51, v53
	v_cndmask_b32_e64 v52, -v52, v52, s[4:5]
	v_cndmask_b32_e64 v53, -v53, v53, s[4:5]
	v_add_f32_e32 v50, v52, v50
	v_add_f32_e32 v51, v53, v51
	v_mov_b32_e32 v52, v112
	v_mov_b32_e32 v53, v111
	s_nop 0
	v_permlane16_swap_b32_e32 v112, v52
	v_permlane16_swap_b32_e32 v111, v53
	v_cndmask_b32_e64 v52, -v52, v52, s[4:5]
	v_cndmask_b32_e64 v53, -v53, v53, s[4:5]
	v_add_f32_e32 v52, v52, v112
	v_add_f32_e32 v53, v53, v111
	v_pk_mul_f32 v[50:51], v[50:51], 0.5 op_sel_hi:[1,0]
	v_pk_mul_f32 v[52:53], v[52:53], 0.5 op_sel_hi:[1,0]
	v_pk_mul_f32 v[50:51], v[50:51], v[56:57] op_sel_hi:[1,0]
	v_pk_mul_f32 v[52:53], v[52:53], v[58:59] op_sel_hi:[1,0]
	v_sub_f32_e32 v110, v138, v142
	v_max3_f32 v53, v57, |v51|, |v53|
	v_max3_f32 v56, v60, |v50|, |v52|
	v_mov_b32_e32 v50, v48
	v_mov_b32_e32 v51, v49
	s_nop 0
	v_permlane16_swap_b32_e32 v48, v50
	v_permlane16_swap_b32_e32 v49, v51
	v_cndmask_b32_e64 v50, -v50, v50, s[4:5]
	v_cndmask_b32_e64 v51, -v51, v51, s[4:5]
	v_add_f32_e32 v48, v50, v48
	v_add_f32_e32 v49, v51, v49
	v_mov_b32_e32 v50, v110
	v_mov_b32_e32 v51, v109
	ds_bpermute_b32 v52, v87, v94
	ds_bpermute_b32 v54, v88, v94
	v_permlane16_swap_b32_e32 v110, v50
	v_permlane16_swap_b32_e32 v109, v51
	v_cndmask_b32_e64 v50, -v50, v50, s[4:5]
	v_cndmask_b32_e64 v51, -v51, v51, s[4:5]
	v_add_f32_e32 v50, v50, v110
	v_add_f32_e32 v51, v51, v109
	v_pk_mul_f32 v[48:49], v[48:49], 0.5 op_sel_hi:[1,0]
	v_pk_mul_f32 v[50:51], v[50:51], 0.5 op_sel_hi:[1,0]
	v_pk_add_f32 v[46:47], v[136:137], v[140:141]
	s_waitcnt lgkmcnt(1)
	v_pk_mul_f32 v[48:49], v[48:49], v[52:53] op_sel_hi:[1,0]
	s_waitcnt lgkmcnt(0)
	v_pk_mul_f32 v[50:51], v[50:51], v[54:55] op_sel_hi:[1,0]
	v_sub_f32_e32 v107, v137, v141
	v_max3_f32 v57, v59, |v48|, |v50|
	v_max3_f32 v51, v55, |v49|, |v51|
	v_mov_b32_e32 v48, v46
	v_mov_b32_e32 v49, v47
	s_nop 0
	v_permlane16_swap_b32_e32 v46, v48
	v_permlane16_swap_b32_e32 v47, v49
	v_sub_f32_e32 v108, v136, v140
	v_cndmask_b32_e64 v48, -v48, v48, s[4:5]
	v_cndmask_b32_e64 v49, -v49, v49, s[4:5]
	v_add_f32_e32 v46, v48, v46
	v_add_f32_e32 v47, v49, v47
	v_mov_b32_e32 v48, v108
	v_mov_b32_e32 v49, v107
	s_nop 0
	v_permlane16_swap_b32_e32 v108, v48
	v_permlane16_swap_b32_e32 v107, v49
	v_cndmask_b32_e64 v48, -v48, v48, s[4:5]
	v_cndmask_b32_e64 v49, -v49, v49, s[4:5]
	v_add_f32_e32 v48, v48, v108
	v_add_f32_e32 v49, v49, v107
	v_pk_mul_f32 v[46:47], v[46:47], 0.5 op_sel_hi:[1,0]
	v_pk_mul_f32 v[48:49], v[48:49], 0.5 op_sel_hi:[1,0]
	s_waitcnt vmcnt(2)
	v_pk_add_f32 v[44:45], v[146:147], v[150:151]
	v_pk_mul_f32 v[46:47], v[46:47], v[52:53] op_sel_hi:[1,0]
	v_pk_mul_f32 v[48:49], v[48:49], v[54:55] op_sel_hi:[1,0]
	v_sub_f32_e32 v104, v147, v151
	v_max3_f32 v52, v56, |v46|, |v48|
	v_max3_f32 v49, v53, |v47|, |v49|
	v_mov_b32_e32 v46, v44
	v_mov_b32_e32 v47, v45
	s_nop 0
	v_permlane16_swap_b32_e32 v44, v46
	v_permlane16_swap_b32_e32 v45, v47
	v_sub_f32_e32 v106, v146, v150
	v_cndmask_b32_e64 v46, -v46, v46, s[4:5]
	v_cndmask_b32_e64 v47, -v47, v47, s[4:5]
	v_add_f32_e32 v44, v46, v44
	v_add_f32_e32 v45, v47, v45
	v_mov_b32_e32 v46, v106
	v_mov_b32_e32 v47, v104
	ds_bpermute_b32 v48, v89, v94
	ds_bpermute_b32 v50, v90, v94
	v_permlane16_swap_b32_e32 v106, v46
	v_permlane16_swap_b32_e32 v104, v47
	v_cndmask_b32_e64 v46, -v46, v46, s[4:5]
	v_cndmask_b32_e64 v47, -v47, v47, s[4:5]
	v_add_f32_e32 v46, v46, v106
	v_add_f32_e32 v47, v47, v104
	v_pk_mul_f32 v[44:45], v[44:45], 0.5 op_sel_hi:[1,0]
	v_pk_mul_f32 v[46:47], v[46:47], 0.5 op_sel_hi:[1,0]
	v_pk_add_f32 v[42:43], v[144:145], v[148:149]
	s_waitcnt lgkmcnt(1)
; __device__ __forceinline__ float bfly16(float x, bool up) { const auto r = __builtin_amdgcn_permlane16_swap(__float_as_uint(x), __float_as_uint(x), false, false); const float a = __uint_as_float(r[0]), b = __uint_as_float(r[1]); return up ? a - b : a + b; }
; __device__ __forceinline__ float bfly32(float x, bool up) { const auto r = __builtin_amdgcn_permlane32_swap(__float_as_uint(x), __float_as_uint(x), false, false); const float a = __uint_as_float(r[0]), b = __uint_as_float(r[1]); return up ? a - b : a + b; }
; template <int ROT>
; __device__ __forceinline__ void gu_absmax(Frame& F, int s_lo, int s_hi) {
;     ...
;             if (ROT) {
; #pragma unroll
;                 for (int st = 1; st <= (ROT <= 3 ? 1 : ROT == 4 ? 2 : 4); st <<= 1)
; #pragma unroll
;                     for (int i = 0; i < 16; ++i) if (!(i & st)) { const f32x4 a = v[i], b = v[i | st]; v[i] = a + b; v[i | st] = a - b; }
;                 { const bool s16 = (lane & 16) != 0, s32 = (lane & 32) != 0;
; #pragma unroll
;                   for (int i = 0; i < 16; ++i)
; #pragma unroll
;                       for (int e = 0; e < 4; ++e) { float x = v[i][e]; if (ROT >= 2) x = bfly16(x, s16); if (ROT >= 3) x = bfly32(x, s32); v[i][e] = x; } }
; #pragma unroll
;                 for (int i = 0; i < 16; ++i) v[i] *= (ROT == 1 ? 0.70710678118654752f : ROT == 2 ? 0.5f : ROT == 3 ? 0.35355339059327373f : ROT == 4 ? 0.25f : 0.17677669529663687f);
;             }
; #pragma unroll
;             for (int i = 0; i < 16; ++i) { const float g = __shfl(gv, 8 * (i >> 1) + 2 * kr + (i & 1)); const f32x4 a = __builtin_elementwise_abs(v[i] * g); cm = __builtin_elementwise_max(cm, a); }
;         }
	v_pk_mul_f32 v[44:45], v[44:45], v[48:49] op_sel_hi:[1,0]
	s_waitcnt lgkmcnt(0)
	v_pk_mul_f32 v[46:47], v[46:47], v[50:51] op_sel_hi:[1,0]
	v_sub_f32_e32 v101, v145, v149
	v_max3_f32 v47, v51, |v45|, |v47|
	v_max3_f32 v51, v57, |v44|, |v46|
	v_mov_b32_e32 v44, v42
	v_mov_b32_e32 v45, v43
	s_nop 0
	v_permlane16_swap_b32_e32 v42, v44
	v_permlane16_swap_b32_e32 v43, v45
	v_sub_f32_e32 v102, v144, v148
	v_cndmask_b32_e64 v44, -v44, v44, s[4:5]
	v_cndmask_b32_e64 v45, -v45, v45, s[4:5]
	v_add_f32_e32 v42, v44, v42
	v_add_f32_e32 v43, v45, v43
	v_mov_b32_e32 v44, v102
	v_mov_b32_e32 v45, v101
	s_nop 0
	v_permlane16_swap_b32_e32 v102, v44
	v_permlane16_swap_b32_e32 v101, v45
	v_cndmask_b32_e64 v44, -v44, v44, s[4:5]
	v_cndmask_b32_e64 v45, -v45, v45, s[4:5]
	v_add_f32_e32 v44, v44, v102
	v_add_f32_e32 v45, v45, v101
	v_pk_mul_f32 v[42:43], v[42:43], 0.5 op_sel_hi:[1,0]
	v_pk_mul_f32 v[44:45], v[44:45], 0.5 op_sel_hi:[1,0]
	s_waitcnt vmcnt(0)
	v_pk_add_f32 v[40:41], v[152:153], v[156:157]
	v_pk_mul_f32 v[42:43], v[42:43], v[48:49] op_sel_hi:[1,0]
	v_pk_mul_f32 v[44:45], v[44:45], v[50:51] op_sel_hi:[1,0]
	v_pk_add_f32 v[38:39], v[154:155], v[158:159]
	v_max3_f32 v50, v52, |v42|, |v44|
	v_mov_b32_e32 v42, v40
	s_nop 1
	v_permlane16_swap_b32_e32 v40, v42
	v_cndmask_b32_e64 v42, -v42, v42, s[4:5]
	v_add_f32_e32 v40, v42, v40
	v_mov_b32_e32 v42, v41
	s_nop 1
	v_permlane16_swap_b32_e32 v41, v42
	v_cndmask_b32_e64 v42, -v42, v42, s[4:5]
	v_add_f32_e32 v41, v42, v41
	v_mov_b32_e32 v42, v38
	s_nop 1
	v_permlane16_swap_b32_e32 v38, v42
	v_cndmask_b32_e64 v42, -v42, v42, s[4:5]
	v_add_f32_e32 v38, v42, v38
	v_mov_b32_e32 v42, v39
	s_nop 1
	v_permlane16_swap_b32_e32 v39, v42
	v_sub_f32_e32 v95, v155, v159
	v_sub_f32_e32 v96, v154, v158
	v_sub_f32_e32 v97, v153, v157
	v_sub_f32_e32 v98, v152, v156
	v_cndmask_b32_e64 v42, -v42, v42, s[4:5]
	v_max3_f32 v49, v49, |v43|, |v45|
	v_add_f32_e32 v39, v42, v39
	v_mov_b32_e32 v42, v98
	v_mov_b32_e32 v43, v97
	v_mov_b32_e32 v44, v96
	v_mov_b32_e32 v45, v95
	ds_bpermute_b32 v46, v91, v94
	ds_bpermute_b32 v48, v92, v94
	v_permlane16_swap_b32_e32 v98, v42
	v_permlane16_swap_b32_e32 v97, v43
	v_permlane16_swap_b32_e32 v96, v44
	v_permlane16_swap_b32_e32 v95, v45
	v_cndmask_b32_e64 v42, -v42, v42, s[4:5]
	v_cndmask_b32_e64 v43, -v43, v43, s[4:5]
	v_cndmask_b32_e64 v44, -v44, v44, s[4:5]
	v_cndmask_b32_e64 v45, -v45, v45, s[4:5]
	v_add_f32_e32 v42, v42, v98
	v_add_f32_e32 v43, v43, v97
	v_add_f32_e32 v44, v44, v96
	v_add_f32_e32 v45, v45, v95
	v_pk_mul_f32 v[38:39], v[38:39], 0.5 op_sel_hi:[1,0]
	v_pk_mul_f32 v[40:41], v[40:41], 0.5 op_sel_hi:[1,0]
	v_pk_mul_f32 v[42:43], v[42:43], 0.5 op_sel_hi:[1,0]
	v_pk_mul_f32 v[44:45], v[44:45], 0.5 op_sel_hi:[1,0]
	s_waitcnt lgkmcnt(1)
	v_pk_mul_f32 v[38:39], v[38:39], v[46:47] op_sel_hi:[1,0]
	v_pk_mul_f32 v[40:41], v[40:41], v[46:47] op_sel_hi:[1,0]
	s_waitcnt lgkmcnt(0)
	v_pk_mul_f32 v[44:45], v[44:45], v[48:49] op_sel_hi:[1,0]
	v_pk_mul_f32 v[42:43], v[42:43], v[48:49] op_sel_hi:[1,0]
	v_max3_f32 v100, v51, |v38|, |v44|
	v_max3_f32 v99, v47, |v39|, |v45|
	v_max3_f32 v103, v50, |v40|, |v42|
	v_max3_f32 v105, v49, |v41|, |v43|
	s_cbranch_scc1 .LBB0_44

; __device__ __forceinline__ float bfly16(float x, bool up) { const auto r = __builtin_amdgcn_permlane16_swap(__float_as_uint(x), __float_as_uint(x), false, false); const float a = __uint_as_float(r[0]), b = __uint_as_float(r[1]); return up ? a - b : a + b; }
; __device__ __forceinline__ float bfly32(float x, bool up) { const auto r = __builtin_amdgcn_permlane32_swap(__float_as_uint(x), __float_as_uint(x), false, false); const float a = __uint_as_float(r[0]), b = __uint_as_float(r[1]); return up ? a - b : a + b; }
; template <int ROT>
; __device__ __forceinline__ void gu_absmax(Frame& F, int s_lo, int s_hi) {
;     ...
;         for (int t = 0; t < ntl; ++t) {
;             const float gv = gain ? gain[512 * kb + 64 * t + lane] : 1.0f;
;             f32x4 v[16];
; #pragma unroll
;             for (int i = 0; i < 16; ++i) v[i] = *(const f32x4*)(src + (size_t)(64 * t + 8 * (i >> 1) + (i & 1)) * rowlen);
;             if (ROT) {
; #pragma unroll
;                 for (int st = 1; st <= (ROT <= 3 ? 1 : ROT == 4 ? 2 : 4); st <<= 1)
; #pragma unroll
;                     for (int i = 0; i < 16; ++i) if (!(i & st)) { const f32x4 a = v[i], b = v[i | st]; v[i] = a + b; v[i | st] = a - b; }
;                 { const bool s16 = (lane & 16) != 0, s32 = (lane & 32) != 0;
; #pragma unroll
;                   for (int i = 0; i < 16; ++i)
; #pragma unroll
;                       for (int e = 0; e < 4; ++e) { float x = v[i][e]; if (ROT >= 2) x = bfly16(x, s16); if (ROT >= 3) x = bfly32(x, s32); v[i][e] = x; } }
; #pragma unroll
;                 for (int i = 0; i < 16; ++i) v[i] *= (ROT == 1 ? 0.70710678118654752f : ROT == 2 ? 0.5f : ROT == 3 ? 0.35355339059327373f : ROT == 4 ? 0.25f : 0.17677669529663687f);
;             }
; #pragma unroll
;             for (int i = 0; i < 16; ++i) { const float g = __shfl(gv, 8 * (i >> 1) + 2 * kr + (i & 1)); const f32x4 a = __builtin_elementwise_abs(v[i] * g); cm = __builtin_elementwise_max(cm, a); }
.LBB0_83:
	v_lshl_add_u64 v[38:39], v[6:7], 0, v[2:3]
	v_lshl_add_u64 v[42:43], v[4:5], 0, v[2:3]
	v_lshl_add_u64 v[54:55], v[34:35], 0, v[2:3]
	v_lshl_add_u64 v[56:57], v[32:33], 0, v[2:3]
	v_lshl_add_u64 v[62:63], v[30:31], 0, v[2:3]
	global_load_dwordx4 v[38:41], v[38:39], off nt
	v_lshl_add_u64 v[90:91], v[28:29], 0, v[2:3]
	global_load_dwordx4 v[42:45], v[42:43], off nt
	s_nop 0
	global_load_dwordx4 v[46:49], v[54:55], off nt
	global_load_dwordx4 v[50:53], v[56:57], off nt
	s_nop 0
	global_load_dwordx4 v[54:57], v[62:63], off nt
	global_load_dwordx4 v[58:61], v[90:91], off nt
	v_lshl_add_u64 v[62:63], v[26:27], 0, v[2:3]
	v_lshl_add_u64 v[98:99], v[24:25], 0, v[2:3]
	global_load_dwordx4 v[90:93], v[62:63], off nt
	global_load_dwordx4 v[94:97], v[98:99], off nt
	v_lshl_add_u64 v[62:63], v[22:23], 0, v[2:3]
	v_lshl_add_u64 v[106:107], v[20:21], 0, v[2:3]
	global_load_dwordx4 v[98:101], v[62:63], off nt
	global_load_dwordx4 v[102:105], v[106:107], off nt
	v_lshl_add_u64 v[62:63], v[18:19], 0, v[2:3]
	v_lshl_add_u64 v[114:115], v[16:17], 0, v[2:3]
	global_load_dwordx4 v[106:109], v[62:63], off nt
	global_load_dwordx4 v[110:113], v[114:115], off nt
	v_lshl_add_u64 v[62:63], v[14:15], 0, v[2:3]
	v_lshl_add_u64 v[122:123], v[12:13], 0, v[2:3]
	global_load_dwordx4 v[114:117], v[62:63], off nt
	global_load_dwordx4 v[118:121], v[122:123], off nt
	v_lshl_add_u64 v[62:63], v[10:11], 0, v[2:3]
	v_lshl_add_u64 v[126:127], v[8:9], 0, v[2:3]
	global_load_dwordx4 v[122:125], v[62:63], off nt
	s_nop 0
	global_load_dwordx4 v[126:129], v[126:127], off nt
	s_add_i32 s17, s17, -1
	v_lshl_add_u64 v[4:5], v[4:5], 0, s[0:1]
	v_lshl_add_u64 v[6:7], v[6:7], 0, s[0:1]
	v_lshl_add_u64 v[8:9], v[8:9], 0, s[0:1]
	v_lshl_add_u64 v[10:11], v[10:11], 0, s[0:1]
	v_lshl_add_u64 v[12:13], v[12:13], 0, s[0:1]
	v_lshl_add_u64 v[14:15], v[14:15], 0, s[0:1]
	v_lshl_add_u64 v[16:17], v[16:17], 0, s[0:1]
	v_lshl_add_u64 v[18:19], v[18:19], 0, s[0:1]
	v_lshl_add_u64 v[20:21], v[20:21], 0, s[0:1]
	v_lshl_add_u64 v[22:23], v[22:23], 0, s[0:1]
	v_lshl_add_u64 v[24:25], v[24:25], 0, s[0:1]
	v_lshl_add_u64 v[26:27], v[26:27], 0, s[0:1]
	v_lshl_add_u64 v[28:29], v[28:29], 0, s[0:1]
	v_lshl_add_u64 v[30:31], v[30:31], 0, s[0:1]
	v_lshl_add_u64 v[32:33], v[32:33], 0, s[0:1]
	v_lshl_add_u64 v[34:35], v[34:35], 0, s[0:1]
	s_cmp_eq_u32 s17, 0
	v_lshl_add_u64 v[36:37], v[36:37], 0, s[14:15]
	s_waitcnt vmcnt(14)
	v_pk_add_f32 v[62:63], v[40:41], v[44:45]
	s_waitcnt vmcnt(12)
	v_pk_add_f32 v[134:135], v[46:47], v[50:51]
	v_sub_f32_e32 v148, v47, v51
	v_sub_f32_e32 v149, v46, v50
	v_sub_f32_e32 v144, v45, v41
	v_sub_f32_e32 v145, v44, v40
	v_pk_add_f32 v[130:131], v[38:39], v[42:43]
	v_sub_f32_e32 v44, v42, v38
	v_pk_add_f32 v[132:133], v[48:49], v[52:53]
	v_sub_f32_e32 v147, v48, v52
	v_mov_b32_e32 v38, v130
	v_mov_b32_e32 v48, v44
	s_nop 0
	v_permlane16_swap_b32_e32 v130, v38
	v_permlane16_swap_b32_e32 v44, v48
	v_sub_f32_e32 v45, v43, v39
	s_waitcnt vmcnt(0)
	v_pk_add_f32 v[46:47], v[122:123], v[126:127]
	v_pk_add_f32 v[40:41], v[124:125], v[128:129]
	v_sub_f32_e32 v128, v124, v128
	v_sub_f32_e32 v124, v122, v126
	v_mov_b32_e32 v126, v46
	s_nop 1
	v_permlane16_swap_b32_e32 v46, v126
	v_cndmask_b32_e64 v126, -v126, v126, s[2:3]
	v_add_f32_e32 v46, v126, v46
	v_mov_b32_e32 v126, v47
	s_nop 1
	v_permlane16_swap_b32_e32 v47, v126
	v_cndmask_b32_e64 v126, -v126, v126, s[2:3]
	v_add_f32_e32 v47, v126, v47
	v_mov_b32_e32 v126, v40
	s_nop 1
	v_permlane16_swap_b32_e32 v40, v126
	v_cndmask_b32_e64 v126, -v126, v126, s[2:3]
	v_add_f32_e32 v40, v126, v40
	v_mov_b32_e32 v126, v41
	s_nop 1
	v_permlane16_swap_b32_e32 v41, v126
	v_cndmask_b32_e64 v126, -v126, v126, s[2:3]
	v_add_f32_e32 v41, v126, v41
	v_mov_b32_e32 v126, v124
	s_nop 1
	v_permlane16_swap_b32_e32 v124, v126
	v_sub_f32_e32 v129, v125, v129
	v_sub_f32_e32 v125, v123, v127
	v_cndmask_b32_e64 v126, -v126, v126, s[2:3]
	v_add_f32_e32 v124, v126, v124
	v_mov_b32_e32 v126, v125
	s_nop 1
	v_permlane16_swap_b32_e32 v125, v126
	v_cndmask_b32_e64 v126, -v126, v126, s[2:3]
	v_add_f32_e32 v125, v126, v125
	v_mov_b32_e32 v126, v128
	s_nop 1
	v_permlane16_swap_b32_e32 v128, v126
	v_cndmask_b32_e64 v38, -v38, v38, s[2:3]
	v_cndmask_b32_e64 v48, -v48, v48, s[2:3]
	v_cndmask_b32_e64 v126, -v126, v126, s[2:3]
	v_mov_b32_e32 v39, v131
	v_add_f32_e32 v38, v38, v130
	v_add_f32_e32 v44, v48, v44
	v_mov_b32_e32 v48, v45
	v_add_f32_e32 v126, v126, v128
	ds_bpermute_b32 v128, v68, v89
	ds_bpermute_b32 v130, v69, v89
	v_permlane16_swap_b32_e32 v131, v39
	v_mov_b32_e32 v42, v62
	v_mov_b32_e32 v43, v63
	v_permlane16_swap_b32_e32 v45, v48
	v_cndmask_b32_e64 v39, -v39, v39, s[2:3]
	v_permlane16_swap_b32_e32 v62, v42
	v_permlane16_swap_b32_e32 v63, v43
	v_cndmask_b32_e64 v48, -v48, v48, s[2:3]
	v_add_f32_e32 v39, v39, v131
	v_cndmask_b32_e64 v42, -v42, v42, s[2:3]
	v_cndmask_b32_e64 v43, -v43, v43, s[2:3]
	v_add_f32_e32 v45, v48, v45
	v_mov_b32_e32 v127, v129
	v_add_f32_e32 v42, v42, v62
	v_add_f32_e32 v43, v43, v63
	v_permlane16_swap_b32_e32 v129, v127
	v_pk_mul_f32 v[38:39], v[38:39], 0.5 op_sel_hi:[1,0]
	v_pk_mul_f32 v[44:45], v[44:45], 0.5 op_sel_hi:[1,0]
	v_sub_f32_e32 v146, v49, v53
	v_mov_b32_e32 v48, v145
	v_mov_b32_e32 v49, v144
	v_pk_mul_f32 v[42:43], v[42:43], 0.5 op_sel_hi:[1,0]
	s_waitcnt lgkmcnt(1)
	v_pk_mul_f32 v[38:39], v[38:39], v[128:129] op_sel_hi:[1,0]
	s_waitcnt lgkmcnt(0)
; __device__ __forceinline__ float bfly16(float x, bool up) { const auto r = __builtin_amdgcn_permlane16_swap(__float_as_uint(x), __float_as_uint(x), false, false); const float a = __uint_as_float(r[0]), b = __uint_as_float(r[1]); return up ? a - b : a + b; }
; __device__ __forceinline__ float bfly32(float x, bool up) { const auto r = __builtin_amdgcn_permlane32_swap(__float_as_uint(x), __float_as_uint(x), false, false); const float a = __uint_as_float(r[0]), b = __uint_as_float(r[1]); return up ? a - b : a + b; }
; template <int ROT>
; __device__ __forceinline__ void gu_absmax(Frame& F, int s_lo, int s_hi) {
;     ...
;                 for (int st = 1; st <= (ROT <= 3 ? 1 : ROT == 4 ? 2 : 4); st <<= 1)
; #pragma unroll
;                     for (int i = 0; i < 16; ++i) if (!(i & st)) { const f32x4 a = v[i], b = v[i | st]; v[i] = a + b; v[i | st] = a - b; }
;                 { const bool s16 = (lane & 16) != 0, s32 = (lane & 32) != 0;
; #pragma unroll
;                   for (int i = 0; i < 16; ++i)
; #pragma unroll
;                       for (int e = 0; e < 4; ++e) { float x = v[i][e]; if (ROT >= 2) x = bfly16(x, s16); if (ROT >= 3) x = bfly32(x, s32); v[i][e] = x; } }
; #pragma unroll
;                 for (int i = 0; i < 16; ++i) v[i] *= (ROT == 1 ? 0.70710678118654752f : ROT == 2 ? 0.5f : ROT == 3 ? 0.35355339059327373f : ROT == 4 ? 0.25f : 0.17677669529663687f);
;             }
; #pragma unroll
;             for (int i = 0; i < 16; ++i) { const float g = __shfl(gv, 8 * (i >> 1) + 2 * kr + (i & 1)); const f32x4 a = __builtin_elementwise_abs(v[i] * g); cm = __builtin_elementwise_max(cm, a); }
	v_pk_mul_f32 v[44:45], v[44:45], v[130:131] op_sel_hi:[1,0]
	v_pk_add_f32 v[138:139], v[54:55], v[58:59]
	v_sub_f32_e32 v152, v55, v59
	v_sub_f32_e32 v153, v54, v58
	v_permlane16_swap_b32_e32 v145, v48
	v_permlane16_swap_b32_e32 v144, v49
	v_mov_b32_e32 v52, v132
	v_mov_b32_e32 v53, v133
	v_mov_b32_e32 v58, v147
	v_mov_b32_e32 v59, v146
	v_pk_mul_f32 v[42:43], v[42:43], v[128:129] op_sel_hi:[1,0]
	v_max3_f32 v128, v88, |v39|, |v45|
	ds_bpermute_b32 v88, v70, v89
	v_max3_f32 v87, v87, |v38|, |v44|
	ds_bpermute_b32 v38, v71, v89
	v_cndmask_b32_e64 v48, -v48, v48, s[2:3]
	v_cndmask_b32_e64 v49, -v49, v49, s[2:3]
	v_mov_b32_e32 v50, v134
	v_mov_b32_e32 v51, v135
	v_permlane16_swap_b32_e32 v132, v52
	v_permlane16_swap_b32_e32 v133, v53
	v_permlane16_swap_b32_e32 v147, v58
	v_permlane16_swap_b32_e32 v146, v59
	v_add_f32_e32 v48, v48, v145
	v_add_f32_e32 v49, v49, v144
	v_permlane16_swap_b32_e32 v134, v50
	v_permlane16_swap_b32_e32 v135, v51
	v_cndmask_b32_e64 v52, -v52, v52, s[2:3]
	v_cndmask_b32_e64 v53, -v53, v53, s[2:3]
	v_cndmask_b32_e64 v58, -v58, v58, s[2:3]
	v_cndmask_b32_e64 v59, -v59, v59, s[2:3]
	v_cndmask_b32_e64 v50, -v50, v50, s[2:3]
	v_cndmask_b32_e64 v51, -v51, v51, s[2:3]
	v_add_f32_e32 v52, v52, v132
	v_add_f32_e32 v53, v53, v133
	v_add_f32_e32 v58, v58, v147
	v_add_f32_e32 v59, v59, v146
	v_pk_mul_f32 v[48:49], v[48:49], 0.5 op_sel_hi:[1,0]
	v_add_f32_e32 v50, v50, v134
	v_add_f32_e32 v51, v51, v135
	v_pk_mul_f32 v[52:53], v[52:53], 0.5 op_sel_hi:[1,0]
	v_pk_mul_f32 v[58:59], v[58:59], 0.5 op_sel_hi:[1,0]
	v_pk_mul_f32 v[48:49], v[48:49], v[130:131] op_sel_hi:[1,0]
	v_pk_add_f32 v[136:137], v[56:57], v[60:61]
	v_sub_f32_e32 v150, v57, v61
	v_sub_f32_e32 v151, v56, v60
	v_mov_b32_e32 v56, v149
	v_mov_b32_e32 v57, v148
	v_pk_mul_f32 v[50:51], v[50:51], 0.5 op_sel_hi:[1,0]
	v_max3_f32 v85, v85, |v43|, |v49|
	v_max3_f32 v86, v86, |v42|, |v48|
	s_waitcnt lgkmcnt(1)
	v_pk_mul_f32 v[42:43], v[52:53], v[88:89] op_sel_hi:[1,0]
	s_waitcnt lgkmcnt(0)
	v_pk_mul_f32 v[48:49], v[58:59], v[38:39] op_sel_hi:[1,0]
	v_pk_add_f32 v[140:141], v[92:93], v[96:97]
	v_sub_f32_e32 v154, v93, v97
	v_sub_f32_e32 v155, v92, v96
	v_pk_add_f32 v[92:93], v[98:99], v[102:103]
	v_sub_f32_e32 v160, v99, v103
	v_sub_f32_e32 v161, v98, v102
	v_permlane16_swap_b32_e32 v149, v56
	v_permlane16_swap_b32_e32 v148, v57
	v_mov_b32_e32 v98, v136
	v_mov_b32_e32 v99, v137
	v_mov_b32_e32 v102, v151
	v_mov_b32_e32 v103, v150
	v_pk_mul_f32 v[44:45], v[50:51], v[88:89] op_sel_hi:[1,0]
	v_max3_f32 v51, v86, |v42|, |v48|
	ds_bpermute_b32 v42, v72, v89
	ds_bpermute_b32 v48, v73, v89
	v_cndmask_b32_e64 v56, -v56, v56, s[2:3]
	v_cndmask_b32_e64 v57, -v57, v57, s[2:3]
	v_permlane16_swap_b32_e32 v136, v98
	v_permlane16_swap_b32_e32 v137, v99
	v_permlane16_swap_b32_e32 v151, v102
	v_permlane16_swap_b32_e32 v150, v103
	v_add_f32_e32 v56, v56, v149
	v_add_f32_e32 v57, v57, v148
	v_cndmask_b32_e64 v98, -v98, v98, s[2:3]
	v_cndmask_b32_e64 v99, -v99, v99, s[2:3]
	v_cndmask_b32_e64 v102, -v102, v102, s[2:3]
	v_cndmask_b32_e64 v103, -v103, v103, s[2:3]
	v_pk_add_f32 v[142:143], v[90:91], v[94:95]
	v_sub_f32_e32 v156, v91, v95
	v_sub_f32_e32 v157, v90, v94
	v_pk_add_f32 v[94:95], v[108:109], v[112:113]
	v_sub_f32_e32 v163, v108, v112
	v_add_f32_e32 v98, v98, v136
	v_add_f32_e32 v99, v99, v137
	v_add_f32_e32 v102, v102, v151
	v_add_f32_e32 v103, v103, v150
	v_mov_b32_e32 v112, v92
	v_pk_mul_f32 v[56:57], v[56:57], 0.5 op_sel_hi:[1,0]
	s_nop 0
	v_permlane16_swap_b32_e32 v92, v112
	v_pk_mul_f32 v[98:99], v[98:99], 0.5 op_sel_hi:[1,0]
	v_pk_mul_f32 v[102:103], v[102:103], 0.5 op_sel_hi:[1,0]
	v_pk_mul_f32 v[38:39], v[56:57], v[38:39] op_sel_hi:[1,0]
	v_pk_add_f32 v[90:91], v[100:101], v[104:105]
	v_sub_f32_e32 v158, v101, v105
	v_sub_f32_e32 v159, v100, v104
	v_pk_add_f32 v[60:61], v[114:115], v[118:119]
	v_mov_b32_e32 v62, v138
	v_mov_b32_e32 v63, v139
	v_mov_b32_e32 v100, v153
	v_mov_b32_e32 v101, v152
	v_cndmask_b32_e64 v112, -v112, v112, s[2:3]
	v_max3_f32 v50, v85, |v43|, |v49|
	v_max3_f32 v52, v87, |v44|, |v38|
	v_max3_f32 v53, v128, |v45|, |v39|
	s_waitcnt lgkmcnt(1)
	v_pk_mul_f32 v[38:39], v[98:99], v[42:43] op_sel_hi:[1,0]
	s_waitcnt lgkmcnt(0)
	v_pk_mul_f32 v[44:45], v[102:103], v[48:49] op_sel_hi:[1,0]
	v_pk_add_f32 v[96:97], v[106:107], v[110:111]
	v_sub_f32_e32 v164, v107, v111
	v_sub_f32_e32 v165, v106, v110
	v_permlane16_swap_b32_e32 v138, v62
	v_permlane16_swap_b32_e32 v139, v63
	v_permlane16_swap_b32_e32 v153, v100
	v_permlane16_swap_b32_e32 v152, v101
	v_mov_b32_e32 v106, v140
	v_mov_b32_e32 v107, v141
	v_mov_b32_e32 v110, v155
	v_mov_b32_e32 v111, v154
	v_add_f32_e32 v92, v112, v92
	v_mov_b32_e32 v112, v93
	v_mov_b32_e32 v122, v60
	v_max3_f32 v56, v50, |v39|, |v45|
	ds_bpermute_b32 v50, v74, v89
	v_max3_f32 v51, v51, |v38|, |v44|
	ds_bpermute_b32 v38, v75, v89
	v_cndmask_b32_e64 v62, -v62, v62, s[2:3]
	v_cndmask_b32_e64 v63, -v63, v63, s[2:3]
	v_cndmask_b32_e64 v100, -v100, v100, s[2:3]
	v_cndmask_b32_e64 v101, -v101, v101, s[2:3]
	v_mov_b32_e32 v104, v142
	v_mov_b32_e32 v105, v143
	v_permlane16_swap_b32_e32 v140, v106
	v_permlane16_swap_b32_e32 v141, v107
	v_permlane16_swap_b32_e32 v155, v110
	v_permlane16_swap_b32_e32 v154, v111
	v_permlane16_swap_b32_e32 v93, v112
	v_permlane16_swap_b32_e32 v60, v122
	v_add_f32_e32 v62, v62, v138
	v_add_f32_e32 v63, v63, v139
	v_add_f32_e32 v100, v100, v153
	v_add_f32_e32 v101, v101, v152
	v_permlane16_swap_b32_e32 v142, v104
	v_permlane16_swap_b32_e32 v143, v105
	v_cndmask_b32_e64 v106, -v106, v106, s[2:3]
	v_cndmask_b32_e64 v107, -v107, v107, s[2:3]
	v_cndmask_b32_e64 v110, -v110, v110, s[2:3]
	v_cndmask_b32_e64 v111, -v111, v111, s[2:3]
; __device__ __forceinline__ float bfly16(float x, bool up) { const auto r = __builtin_amdgcn_permlane16_swap(__float_as_uint(x), __float_as_uint(x), false, false); const float a = __uint_as_float(r[0]), b = __uint_as_float(r[1]); return up ? a - b : a + b; }
; __device__ __forceinline__ float bfly32(float x, bool up) { const auto r = __builtin_amdgcn_permlane32_swap(__float_as_uint(x), __float_as_uint(x), false, false); const float a = __uint_as_float(r[0]), b = __uint_as_float(r[1]); return up ? a - b : a + b; }
; template <int ROT>
; __device__ __forceinline__ void gu_absmax(Frame& F, int s_lo, int s_hi) {
;     ...
;                 for (int st = 1; st <= (ROT <= 3 ? 1 : ROT == 4 ? 2 : 4); st <<= 1)
; #pragma unroll
;                     for (int i = 0; i < 16; ++i) if (!(i & st)) { const f32x4 a = v[i], b = v[i | st]; v[i] = a + b; v[i | st] = a - b; }
;                 { const bool s16 = (lane & 16) != 0, s32 = (lane & 32) != 0;
; #pragma unroll
;                   for (int i = 0; i < 16; ++i)
; #pragma unroll
;                       for (int e = 0; e < 4; ++e) { float x = v[i][e]; if (ROT >= 2) x = bfly16(x, s16); if (ROT >= 3) x = bfly32(x, s32); v[i][e] = x; } }
; #pragma unroll
;                 for (int i = 0; i < 16; ++i) v[i] *= (ROT == 1 ? 0.70710678118654752f : ROT == 2 ? 0.5f : ROT == 3 ? 0.35355339059327373f : ROT == 4 ? 0.25f : 0.17677669529663687f);
;             }
; #pragma unroll
;             for (int i = 0; i < 16; ++i) { const float g = __shfl(gv, 8 * (i >> 1) + 2 * kr + (i & 1)); const f32x4 a = __builtin_elementwise_abs(v[i] * g); cm = __builtin_elementwise_max(cm, a); }
	v_cndmask_b32_e64 v112, -v112, v112, s[2:3]
	v_cndmask_b32_e64 v122, -v122, v122, s[2:3]
	v_pk_add_f32 v[54:55], v[116:117], v[120:121]
	v_sub_f32_e32 v167, v116, v120
	v_cndmask_b32_e64 v104, -v104, v104, s[2:3]
	v_cndmask_b32_e64 v105, -v105, v105, s[2:3]
	v_add_f32_e32 v106, v106, v140
	v_add_f32_e32 v107, v107, v141
	v_add_f32_e32 v110, v110, v155
	v_add_f32_e32 v111, v111, v154
	v_add_f32_e32 v93, v112, v93
	v_mov_b32_e32 v112, v90
	v_mov_b32_e32 v116, v96
	v_add_f32_e32 v60, v122, v60
	v_mov_b32_e32 v122, v61
	v_pk_mul_f32 v[62:63], v[62:63], 0.5 op_sel_hi:[1,0]
	v_pk_mul_f32 v[100:101], v[100:101], 0.5 op_sel_hi:[1,0]
	v_add_f32_e32 v104, v104, v142
	v_add_f32_e32 v105, v105, v143
	v_permlane16_swap_b32_e32 v90, v112
	v_permlane16_swap_b32_e32 v96, v116
	v_permlane16_swap_b32_e32 v61, v122
	v_pk_mul_f32 v[106:107], v[106:107], 0.5 op_sel_hi:[1,0]
	v_pk_mul_f32 v[110:111], v[110:111], 0.5 op_sel_hi:[1,0]
	v_pk_mul_f32 v[42:43], v[62:63], v[42:43] op_sel_hi:[1,0]
	v_pk_mul_f32 v[48:49], v[100:101], v[48:49] op_sel_hi:[1,0]
	v_sub_f32_e32 v162, v109, v113
	v_mov_b32_e32 v108, v157
	v_mov_b32_e32 v109, v156
	v_cndmask_b32_e64 v112, -v112, v112, s[2:3]
	v_cndmask_b32_e64 v116, -v116, v116, s[2:3]
	v_cndmask_b32_e64 v122, -v122, v122, s[2:3]
	v_pk_mul_f32 v[104:105], v[104:105], 0.5 op_sel_hi:[1,0]
	v_max3_f32 v53, v53, |v43|, |v49|
	v_max3_f32 v52, v52, |v42|, |v48|
	s_waitcnt lgkmcnt(1)
	v_pk_mul_f32 v[42:43], v[106:107], v[50:51] op_sel_hi:[1,0]
	s_waitcnt lgkmcnt(0)
	v_pk_mul_f32 v[48:49], v[110:111], v[38:39] op_sel_hi:[1,0]
	v_sub_f32_e32 v166, v117, v121
	v_sub_f32_e32 v121, v115, v119
	v_sub_f32_e32 v120, v114, v118
	v_permlane16_swap_b32_e32 v157, v108
	v_permlane16_swap_b32_e32 v156, v109
	v_add_f32_e32 v90, v112, v90
	v_mov_b32_e32 v112, v91
	v_mov_b32_e32 v114, v159
	v_mov_b32_e32 v115, v158
	v_add_f32_e32 v96, v116, v96
	v_mov_b32_e32 v116, v97
	v_add_f32_e32 v61, v122, v61
	v_mov_b32_e32 v122, v54
	v_pk_mul_f32 v[44:45], v[104:105], v[50:51] op_sel_hi:[1,0]
	v_max3_f32 v51, v51, |v42|, |v48|
	ds_bpermute_b32 v42, v76, v89
	ds_bpermute_b32 v48, v77, v89
	v_cndmask_b32_e64 v108, -v108, v108, s[2:3]
	v_cndmask_b32_e64 v109, -v109, v109, s[2:3]
	v_permlane16_swap_b32_e32 v91, v112
	v_permlane16_swap_b32_e32 v159, v114
	v_permlane16_swap_b32_e32 v158, v115
	v_permlane16_swap_b32_e32 v97, v116
	v_permlane16_swap_b32_e32 v54, v122
	v_add_f32_e32 v108, v108, v157
	v_add_f32_e32 v109, v109, v156
	v_cndmask_b32_e64 v112, -v112, v112, s[2:3]
	v_cndmask_b32_e64 v114, -v114, v114, s[2:3]
	v_cndmask_b32_e64 v115, -v115, v115, s[2:3]
	v_cndmask_b32_e64 v116, -v116, v116, s[2:3]
	v_cndmask_b32_e64 v122, -v122, v122, s[2:3]
	v_add_f32_e32 v91, v112, v91
	v_add_f32_e32 v114, v114, v159
	v_add_f32_e32 v115, v115, v158
	v_add_f32_e32 v97, v116, v97
	v_mov_b32_e32 v116, v94
	v_add_f32_e32 v54, v122, v54
	v_mov_b32_e32 v122, v55
	v_pk_mul_f32 v[108:109], v[108:109], 0.5 op_sel_hi:[1,0]
	v_permlane16_swap_b32_e32 v94, v116
	v_permlane16_swap_b32_e32 v55, v122
	v_pk_mul_f32 v[90:91], v[90:91], 0.5 op_sel_hi:[1,0]
	v_pk_mul_f32 v[114:115], v[114:115], 0.5 op_sel_hi:[1,0]
	v_pk_mul_f32 v[38:39], v[108:109], v[38:39] op_sel_hi:[1,0]
	v_mov_b32_e32 v112, v161
	v_mov_b32_e32 v113, v160
	v_cndmask_b32_e64 v116, -v116, v116, s[2:3]
	v_cndmask_b32_e64 v122, -v122, v122, s[2:3]
	v_max3_f32 v50, v56, |v43|, |v49|
	v_max3_f32 v52, v52, |v44|, |v38|
	v_max3_f32 v53, v53, |v45|, |v39|
	s_waitcnt lgkmcnt(1)
	v_pk_mul_f32 v[38:39], v[90:91], v[42:43] op_sel_hi:[1,0]
	s_waitcnt lgkmcnt(0)
; __device__ __forceinline__ float bfly16(float x, bool up) { const auto r = __builtin_amdgcn_permlane16_swap(__float_as_uint(x), __float_as_uint(x), false, false); const float a = __uint_as_float(r[0]), b = __uint_as_float(r[1]); return up ? a - b : a + b; }
; __device__ __forceinline__ float bfly32(float x, bool up) { const auto r = __builtin_amdgcn_permlane32_swap(__float_as_uint(x), __float_as_uint(x), false, false); const float a = __uint_as_float(r[0]), b = __uint_as_float(r[1]); return up ? a - b : a + b; }
; template <int ROT>
; __device__ __forceinline__ void gu_absmax(Frame& F, int s_lo, int s_hi) {
;     ...
;                 for (int st = 1; st <= (ROT <= 3 ? 1 : ROT == 4 ? 2 : 4); st <<= 1)
; #pragma unroll
;                     for (int i = 0; i < 16; ++i) if (!(i & st)) { const f32x4 a = v[i], b = v[i | st]; v[i] = a + b; v[i | st] = a - b; }
;                 { const bool s16 = (lane & 16) != 0, s32 = (lane & 32) != 0;
; #pragma unroll
;                   for (int i = 0; i < 16; ++i)
; #pragma unroll
;                       for (int e = 0; e < 4; ++e) { float x = v[i][e]; if (ROT >= 2) x = bfly16(x, s16); if (ROT >= 3) x = bfly32(x, s32); v[i][e] = x; } }
; #pragma unroll
;                 for (int i = 0; i < 16; ++i) v[i] *= (ROT == 1 ? 0.70710678118654752f : ROT == 2 ? 0.5f : ROT == 3 ? 0.35355339059327373f : ROT == 4 ? 0.25f : 0.17677669529663687f);
;             }
; #pragma unroll
;             for (int i = 0; i < 16; ++i) { const float g = __shfl(gv, 8 * (i >> 1) + 2 * kr + (i & 1)); const f32x4 a = __builtin_elementwise_abs(v[i] * g); cm = __builtin_elementwise_max(cm, a); }
;         }
; #pragma unroll
;         for (int e = 0; e < 4; ++e) { float c = cm[e]; c = fmaxf(c, __shfl_xor(c, 16)); c = fmaxf(c, __shfl_xor(c, 32)); cm[e] = c; }
	v_pk_mul_f32 v[44:45], v[114:115], v[48:49] op_sel_hi:[1,0]
	v_permlane16_swap_b32_e32 v161, v112
	v_permlane16_swap_b32_e32 v160, v113
	v_add_f32_e32 v94, v116, v94
	v_mov_b32_e32 v116, v95
	v_mov_b32_e32 v118, v163
	v_mov_b32_e32 v119, v162
	v_add_f32_e32 v55, v122, v55
	v_mov_b32_e32 v122, v120
	v_max3_f32 v56, v50, |v39|, |v45|
	ds_bpermute_b32 v50, v78, v89
	v_max3_f32 v51, v51, |v38|, |v44|
	ds_bpermute_b32 v38, v79, v89
	v_cndmask_b32_e64 v112, -v112, v112, s[2:3]
	v_cndmask_b32_e64 v113, -v113, v113, s[2:3]
	v_permlane16_swap_b32_e32 v95, v116
	v_permlane16_swap_b32_e32 v163, v118
	v_permlane16_swap_b32_e32 v162, v119
	v_permlane16_swap_b32_e32 v120, v122
	v_add_f32_e32 v112, v112, v161
	v_add_f32_e32 v113, v113, v160
	v_cndmask_b32_e64 v116, -v116, v116, s[2:3]
	v_cndmask_b32_e64 v118, -v118, v118, s[2:3]
	v_cndmask_b32_e64 v119, -v119, v119, s[2:3]
	v_cndmask_b32_e64 v122, -v122, v122, s[2:3]
	v_add_f32_e32 v95, v116, v95
	v_add_f32_e32 v118, v118, v163
	v_add_f32_e32 v119, v119, v162
	v_add_f32_e32 v120, v122, v120
	v_mov_b32_e32 v122, v121
	v_pk_mul_f32 v[92:93], v[92:93], 0.5 op_sel_hi:[1,0]
	v_pk_mul_f32 v[112:113], v[112:113], 0.5 op_sel_hi:[1,0]
	v_permlane16_swap_b32_e32 v121, v122
	v_pk_mul_f32 v[94:95], v[94:95], 0.5 op_sel_hi:[1,0]
	v_pk_mul_f32 v[118:119], v[118:119], 0.5 op_sel_hi:[1,0]
	v_pk_mul_f32 v[42:43], v[92:93], v[42:43] op_sel_hi:[1,0]
	v_pk_mul_f32 v[48:49], v[112:113], v[48:49] op_sel_hi:[1,0]
	v_mov_b32_e32 v116, v165
	v_mov_b32_e32 v117, v164
	v_cndmask_b32_e64 v122, -v122, v122, s[2:3]
	v_pk_mul_f32 v[96:97], v[96:97], 0.5 op_sel_hi:[1,0]
	v_max3_f32 v53, v53, |v43|, |v49|
	v_max3_f32 v52, v52, |v42|, |v48|
	s_waitcnt lgkmcnt(1)
	v_pk_mul_f32 v[42:43], v[94:95], v[50:51] op_sel_hi:[1,0]
	s_waitcnt lgkmcnt(0)
	v_pk_mul_f32 v[48:49], v[118:119], v[38:39] op_sel_hi:[1,0]
	v_permlane16_swap_b32_e32 v165, v116
	v_permlane16_swap_b32_e32 v164, v117
	v_add_f32_e32 v121, v122, v121
	v_mov_b32_e32 v122, v167
	v_mov_b32_e32 v123, v166
	v_pk_mul_f32 v[44:45], v[96:97], v[50:51] op_sel_hi:[1,0]
	v_max3_f32 v51, v51, |v42|, |v48|
	ds_bpermute_b32 v42, v80, v89
	ds_bpermute_b32 v48, v81, v89
	v_cndmask_b32_e64 v116, -v116, v116, s[2:3]
	v_cndmask_b32_e64 v117, -v117, v117, s[2:3]
	v_permlane16_swap_b32_e32 v167, v122
	v_permlane16_swap_b32_e32 v166, v123
	v_add_f32_e32 v116, v116, v165
	v_add_f32_e32 v117, v117, v164
	v_cndmask_b32_e64 v122, -v122, v122, s[2:3]
	v_cndmask_b32_e64 v123, -v123, v123, s[2:3]
	v_add_f32_e32 v122, v122, v167
	v_add_f32_e32 v123, v123, v166
	v_pk_mul_f32 v[116:117], v[116:117], 0.5 op_sel_hi:[1,0]
	v_pk_mul_f32 v[54:55], v[54:55], 0.5 op_sel_hi:[1,0]
	v_pk_mul_f32 v[122:123], v[122:123], 0.5 op_sel_hi:[1,0]
	v_pk_mul_f32 v[38:39], v[116:117], v[38:39] op_sel_hi:[1,0]
	v_max3_f32 v50, v56, |v43|, |v49|
	v_max3_f32 v52, v52, |v44|, |v38|
	v_max3_f32 v53, v53, |v45|, |v39|
	s_waitcnt lgkmcnt(1)
	v_pk_mul_f32 v[38:39], v[54:55], v[42:43] op_sel_hi:[1,0]
	s_waitcnt lgkmcnt(0)
	v_pk_mul_f32 v[44:45], v[122:123], v[48:49] op_sel_hi:[1,0]
	v_cndmask_b32_e64 v127, -v127, v127, s[2:3]
	v_max3_f32 v54, v50, |v39|, |v45|
	ds_bpermute_b32 v50, v82, v89
	v_max3_f32 v51, v51, |v38|, |v44|
	ds_bpermute_b32 v38, v83, v89
	v_add_f32_e32 v127, v127, v129
	v_pk_mul_f32 v[60:61], v[60:61], 0.5 op_sel_hi:[1,0]
	v_pk_mul_f32 v[120:121], v[120:121], 0.5 op_sel_hi:[1,0]
	v_pk_mul_f32 v[40:41], v[40:41], 0.5 op_sel_hi:[1,0]
	v_pk_mul_f32 v[46:47], v[46:47], 0.5 op_sel_hi:[1,0]
	v_pk_mul_f32 v[124:125], v[124:125], 0.5 op_sel_hi:[1,0]
	v_pk_mul_f32 v[126:127], v[126:127], 0.5 op_sel_hi:[1,0]
	v_pk_mul_f32 v[42:43], v[60:61], v[42:43] op_sel_hi:[1,0]
	v_pk_mul_f32 v[48:49], v[120:121], v[48:49] op_sel_hi:[1,0]
	s_waitcnt lgkmcnt(1)
	v_pk_mul_f32 v[40:41], v[40:41], v[50:51] op_sel_hi:[1,0]
	v_max3_f32 v49, v53, |v43|, |v49|
	v_max3_f32 v48, v52, |v42|, |v48|
	v_pk_mul_f32 v[42:43], v[46:47], v[50:51] op_sel_hi:[1,0]
	s_waitcnt lgkmcnt(0)
	v_pk_mul_f32 v[44:45], v[126:127], v[38:39] op_sel_hi:[1,0]
	v_pk_mul_f32 v[38:39], v[124:125], v[38:39] op_sel_hi:[1,0]
	v_max3_f32 v86, v51, |v40|, |v44|
	v_max3_f32 v85, v54, |v41|, |v45|
	v_max3_f32 v87, v48, |v42|, |v38|
	v_max3_f32 v88, v49, |v43|, |v39|
	s_cbranch_scc1 .LBB0_89

; __device__ __forceinline__ float bfly16(float x, bool up) { const auto r = __builtin_amdgcn_permlane16_swap(__float_as_uint(x), __float_as_uint(x), false, false); const float a = __uint_as_float(r[0]), b = __uint_as_float(r[1]); return up ? a - b : a + b; }
; __device__ __forceinline__ float bfly32(float x, bool up) { const auto r = __builtin_amdgcn_permlane32_swap(__float_as_uint(x), __float_as_uint(x), false, false); const float a = __uint_as_float(r[0]), b = __uint_as_float(r[1]); return up ? a - b : a + b; }
; template <int ROT>
; __device__ __forceinline__ void gu_absmax(Frame& F, int s_lo, int s_hi) {
;     ...
;         for (int t = 0; t < ntl; ++t) {
;             const float gv = gain ? gain[512 * kb + 64 * t + lane] : 1.0f;
;             f32x4 v[16];
; #pragma unroll
;             for (int i = 0; i < 16; ++i) v[i] = *(const f32x4*)(src + (size_t)(64 * t + 8 * (i >> 1) + (i & 1)) * rowlen);
;             if (ROT) {
; #pragma unroll
;                 for (int st = 1; st <= (ROT <= 3 ? 1 : ROT == 4 ? 2 : 4); st <<= 1)
; #pragma unroll
;                     for (int i = 0; i < 16; ++i) if (!(i & st)) { const f32x4 a = v[i], b = v[i | st]; v[i] = a + b; v[i | st] = a - b; }
;                 { const bool s16 = (lane & 16) != 0, s32 = (lane & 32) != 0;
; #pragma unroll
;                   for (int i = 0; i < 16; ++i)
; #pragma unroll
;                       for (int e = 0; e < 4; ++e) { float x = v[i][e]; if (ROT >= 2) x = bfly16(x, s16); if (ROT >= 3) x = bfly32(x, s32); v[i][e] = x; } }
; #pragma unroll
;                 for (int i = 0; i < 16; ++i) v[i] *= (ROT == 1 ? 0.70710678118654752f : ROT == 2 ? 0.5f : ROT == 3 ? 0.35355339059327373f : ROT == 4 ? 0.25f : 0.17677669529663687f);
;             }
; #pragma unroll
;             for (int i = 0; i < 16; ++i) { const float g = __shfl(gv, 8 * (i >> 1) + 2 * kr + (i & 1)); const f32x4 a = __builtin_elementwise_abs(v[i] * g); cm = __builtin_elementwise_max(cm, a); }
.LBB0_99:
	s_waitcnt vmcnt(15) lgkmcnt(14)
	v_pk_mul_f32 v[64:65], v[64:65], v[104:105] op_sel_hi:[1,0]
	v_pk_mul_f32 v[62:63], v[62:63], v[104:105] op_sel_hi:[1,0]
	s_waitcnt vmcnt(14)
	v_pk_mul_f32 v[52:53], v[52:53], v[102:103] op_sel_hi:[1,0]
	v_pk_mul_f32 v[50:51], v[50:51], v[102:103] op_sel_hi:[1,0]
	v_max3_f32 v65, v113, |v65|, |v53|
	v_max3_f32 v64, v114, |v64|, |v52|
	v_max3_f32 v63, v116, |v63|, |v51|
	v_max3_f32 v62, v115, |v62|, |v50|
	s_waitcnt vmcnt(13) lgkmcnt(13)
	v_pk_mul_f32 v[50:51], v[60:61], v[100:101] op_sel_hi:[1,0]
	v_pk_mul_f32 v[52:53], v[58:59], v[100:101] op_sel_hi:[1,0]
	s_waitcnt vmcnt(12) lgkmcnt(12)
	v_pk_mul_f32 v[44:45], v[44:45], v[98:99] op_sel_hi:[1,0]
	v_pk_mul_f32 v[42:43], v[42:43], v[98:99] op_sel_hi:[1,0]
	v_max3_f32 v50, v64, |v50|, |v44|
	v_max3_f32 v51, v65, |v51|, |v45|
	v_max3_f32 v52, v62, |v52|, |v42|
	v_max3_f32 v53, v63, |v53|, |v43|
	s_waitcnt vmcnt(11) lgkmcnt(11)
	v_pk_mul_f32 v[42:43], v[56:57], v[96:97] op_sel_hi:[1,0]
	v_pk_mul_f32 v[44:45], v[54:55], v[96:97] op_sel_hi:[1,0]
	s_waitcnt vmcnt(10) lgkmcnt(10)
	v_pk_mul_f32 v[36:37], v[36:37], v[94:95] op_sel_hi:[1,0]
	v_pk_mul_f32 v[34:35], v[34:35], v[94:95] op_sel_hi:[1,0]
	v_max3_f32 v43, v51, |v43|, |v37|
	v_max3_f32 v42, v50, |v42|, |v36|
	v_max3_f32 v45, v53, |v45|, |v35|
	v_max3_f32 v44, v52, |v44|, |v34|
	s_waitcnt vmcnt(9) lgkmcnt(9)
	v_pk_mul_f32 v[34:35], v[48:49], v[92:93] op_sel_hi:[1,0]
	v_pk_mul_f32 v[36:37], v[46:47], v[92:93] op_sel_hi:[1,0]
	s_waitcnt vmcnt(8) lgkmcnt(8)
	v_pk_mul_f32 v[28:29], v[28:29], v[90:91] op_sel_hi:[1,0]
	v_pk_mul_f32 v[26:27], v[26:27], v[90:91] op_sel_hi:[1,0]
	v_max3_f32 v34, v42, |v34|, |v28|
	v_max3_f32 v35, v43, |v35|, |v29|
	v_max3_f32 v36, v44, |v36|, |v26|
	v_max3_f32 v37, v45, |v37|, |v27|
	s_waitcnt vmcnt(7) lgkmcnt(7)
	v_pk_mul_f32 v[26:27], v[40:41], v[88:89] op_sel_hi:[1,0]
	v_pk_mul_f32 v[28:29], v[38:39], v[88:89] op_sel_hi:[1,0]
	s_waitcnt vmcnt(6) lgkmcnt(6)
	v_pk_mul_f32 v[20:21], v[20:21], v[86:87] op_sel_hi:[1,0]
	v_pk_mul_f32 v[18:19], v[18:19], v[86:87] op_sel_hi:[1,0]
	v_max3_f32 v27, v35, |v27|, |v21|
	v_max3_f32 v26, v34, |v26|, |v20|
	v_max3_f32 v29, v37, |v29|, |v19|
	v_max3_f32 v28, v36, |v28|, |v18|
	s_waitcnt vmcnt(5) lgkmcnt(5)
	v_pk_mul_f32 v[18:19], v[32:33], v[84:85] op_sel_hi:[1,0]
	v_pk_mul_f32 v[20:21], v[30:31], v[84:85] op_sel_hi:[1,0]
	s_waitcnt vmcnt(4) lgkmcnt(4)
	v_pk_mul_f32 v[12:13], v[12:13], v[82:83] op_sel_hi:[1,0]
	v_pk_mul_f32 v[10:11], v[10:11], v[82:83] op_sel_hi:[1,0]
	s_waitcnt vmcnt(0) lgkmcnt(0)
	v_pk_mul_f32 v[120:121], v[4:5], v[74:75] op_sel_hi:[1,0]
	v_add_co_u32_e32 v4, vcc, s18, v72
	v_max3_f32 v18, v26, |v18|, |v12|
	v_max3_f32 v20, v28, |v20|, |v10|
	v_max3_f32 v21, v29, |v21|, |v11|
	v_pk_mul_f32 v[10:11], v[24:25], v[80:81] op_sel_hi:[1,0]
	v_pk_mul_f32 v[8:9], v[8:9], v[78:79] op_sel_hi:[1,0]
	v_addc_co_u32_e32 v5, vcc, 0, v73, vcc
	v_max3_f32 v19, v27, |v19|, |v13|
	v_pk_mul_f32 v[12:13], v[22:23], v[80:81] op_sel_hi:[1,0]
	v_max3_f32 v80, v18, |v10|, |v8|
	v_add_co_u32_e32 v8, vcc, s19, v72
	v_pk_mul_f32 v[6:7], v[6:7], v[78:79] op_sel_hi:[1,0]
	v_max3_f32 v78, v19, |v11|, |v9|
	v_addc_co_u32_e32 v9, vcc, 0, v73, vcc
	v_max3_f32 v82, v21, |v13|, |v7|
	v_max3_f32 v84, v20, |v12|, |v6|
	global_load_dwordx4 v[4:7], v[4:5], off nt
	v_add_co_u32_e32 v12, vcc, s20, v72
	global_load_dwordx4 v[8:11], v[8:9], off offset:3072 nt
	s_nop 0
	v_addc_co_u32_e32 v13, vcc, 0, v73, vcc
	v_pk_mul_f32 v[64:65], v[16:17], v[76:77] op_sel_hi:[1,0]
	v_add_co_u32_e32 v16, vcc, s21, v72
	v_pk_mul_f32 v[118:119], v[14:15], v[76:77] op_sel_hi:[1,0]
	s_nop 0
	v_addc_co_u32_e32 v17, vcc, 0, v73, vcc
	global_load_dwordx4 v[12:15], v[12:13], off nt
	v_add_co_u32_e32 v20, vcc, s22, v72
	global_load_dwordx4 v[16:19], v[16:17], off offset:3072 nt
	s_nop 0
	v_addc_co_u32_e32 v21, vcc, 0, v73, vcc
	v_add_co_u32_e32 v24, vcc, s23, v72
	global_load_dwordx4 v[20:23], v[20:21], off nt
	s_nop 0
	v_addc_co_u32_e32 v25, vcc, 0, v73, vcc
	global_load_dwordx4 v[24:27], v[24:25], off offset:3072 nt
	v_add_co_u32_e32 v28, vcc, s24, v72
	v_pk_mul_f32 v[2:3], v[2:3], v[74:75] op_sel_hi:[1,0]
	s_nop 0
	v_addc_co_u32_e32 v29, vcc, 0, v73, vcc
	v_add_co_u32_e32 v32, vcc, s25, v72
	global_load_dwordx4 v[28:31], v[28:29], off nt
	s_nop 0
	v_addc_co_u32_e32 v33, vcc, 0, v73, vcc
	global_load_dwordx4 v[32:35], v[32:33], off offset:3072 nt
	v_add_co_u32_e32 v36, vcc, s26, v72
	v_max3_f32 v65, v78, |v65|, |v121|
	s_nop 0
	v_addc_co_u32_e32 v37, vcc, 0, v73, vcc
	v_add_co_u32_e32 v40, vcc, s27, v72
	global_load_dwordx4 v[36:39], v[36:37], off nt
	s_nop 0
	v_addc_co_u32_e32 v41, vcc, 0, v73, vcc
	global_load_dwordx4 v[40:43], v[40:41], off offset:3072 nt
	v_add_co_u32_e32 v44, vcc, s28, v72
	v_max3_f32 v74, v84, |v118|, |v2|
	s_nop 0
	v_addc_co_u32_e32 v45, vcc, 0, v73, vcc
	v_add_co_u32_e32 v48, vcc, s29, v72
	global_load_dwordx4 v[44:47], v[44:45], off nt
	s_nop 0
	v_addc_co_u32_e32 v49, vcc, 0, v73, vcc
	global_load_dwordx4 v[48:51], v[48:49], off offset:3072 nt
	v_add_co_u32_e32 v52, vcc, s30, v72
	v_max3_f32 v76, v82, |v119|, |v3|
	s_nop 0
	v_addc_co_u32_e32 v53, vcc, 0, v73, vcc
	v_add_co_u32_e32 v56, vcc, s31, v72
	global_load_dwordx4 v[52:55], v[52:53], off nt
	s_nop 0
	v_addc_co_u32_e32 v57, vcc, 0, v73, vcc
	global_load_dwordx4 v[56:59], v[56:57], off offset:3072 nt
	v_add_co_u32_e32 v60, vcc, s33, v72
	s_add_u32 s6, s6, 0x560000
	s_nop 0
	v_addc_co_u32_e32 v61, vcc, 0, v73, vcc
	v_add_co_u32_e32 v72, vcc, s35, v72
	global_load_dwordx4 v[60:63], v[60:61], off nt
	s_nop 0
	v_addc_co_u32_e32 v73, vcc, 0, v73, vcc
	global_load_dwordx4 v[114:117], v[72:73], off offset:3072 nt
	v_max3_f32 v73, v80, |v64|, |v120|
	ds_bpermute_b32 v64, v83, v112
	ds_bpermute_b32 v72, v85, v112
	s_addc_u32 s7, s7, 0
	v_lshl_add_u64 v[66:67], v[66:67], 0, s[0:1]
	s_cmp_lg_u32 s6, 0x1580000
	s_waitcnt vmcnt(15) lgkmcnt(1)
; template <int ROT>
; __device__ __forceinline__ void gu_absmax(Frame& F, int s_lo, int s_hi) {
;     ...
; #pragma unroll
;             for (int i = 0; i < 16; ++i) { const float g = __shfl(gv, 8 * (i >> 1) + 2 * kr + (i & 1)); const f32x4 a = __builtin_elementwise_abs(v[i] * g); cm = __builtin_elementwise_max(cm, a); }
	v_pk_mul_f32 v[2:3], v[6:7], v[64:65] op_sel_hi:[1,0]
	s_waitcnt vmcnt(14) lgkmcnt(0)
	v_pk_mul_f32 v[6:7], v[10:11], v[72:73] op_sel_hi:[1,0]
	v_pk_mul_f32 v[4:5], v[4:5], v[64:65] op_sel_hi:[1,0]
	ds_bpermute_b32 v10, v87, v112
	v_max3_f32 v64, v73, |v2|, |v6|
	ds_bpermute_b32 v2, v89, v112
	v_pk_mul_f32 v[8:9], v[8:9], v[72:73] op_sel_hi:[1,0]
	v_max3_f32 v11, v65, |v3|, |v7|
	v_max3_f32 v65, v76, |v5|, |v9|
	v_max3_f32 v72, v74, |v4|, |v8|
	s_waitcnt vmcnt(13) lgkmcnt(1)
	v_pk_mul_f32 v[4:5], v[14:15], v[10:11] op_sel_hi:[1,0]
	s_waitcnt vmcnt(12) lgkmcnt(0)
	v_pk_mul_f32 v[8:9], v[18:19], v[2:3] op_sel_hi:[1,0]
	v_pk_mul_f32 v[6:7], v[12:13], v[10:11] op_sel_hi:[1,0]
	v_max3_f32 v12, v64, |v4|, |v8|
	ds_bpermute_b32 v4, v91, v112
	ds_bpermute_b32 v8, v93, v112
	v_pk_mul_f32 v[2:3], v[16:17], v[2:3] op_sel_hi:[1,0]
	v_max3_f32 v10, v11, |v5|, |v9|
	v_max3_f32 v11, v72, |v6|, |v2|
	v_max3_f32 v13, v65, |v7|, |v3|
	s_waitcnt vmcnt(11) lgkmcnt(1)
	v_pk_mul_f32 v[2:3], v[22:23], v[4:5] op_sel_hi:[1,0]
	s_waitcnt vmcnt(10) lgkmcnt(0)
	v_pk_mul_f32 v[6:7], v[26:27], v[8:9] op_sel_hi:[1,0]
	v_pk_mul_f32 v[4:5], v[20:21], v[4:5] op_sel_hi:[1,0]
	v_max3_f32 v14, v10, |v3|, |v7|
	ds_bpermute_b32 v10, v95, v112
	v_max3_f32 v12, v12, |v2|, |v6|
	ds_bpermute_b32 v2, v97, v112
	v_pk_mul_f32 v[8:9], v[24:25], v[8:9] op_sel_hi:[1,0]
	v_lshl_add_u64 v[68:69], v[68:69], 0, s[0:1]
	v_max3_f32 v11, v11, |v4|, |v8|
	v_max3_f32 v13, v13, |v5|, |v9|
	s_waitcnt vmcnt(9) lgkmcnt(1)
	v_pk_mul_f32 v[4:5], v[30:31], v[10:11] op_sel_hi:[1,0]
	s_waitcnt vmcnt(8) lgkmcnt(0)
	v_pk_mul_f32 v[8:9], v[34:35], v[2:3] op_sel_hi:[1,0]
	v_pk_mul_f32 v[6:7], v[28:29], v[10:11] op_sel_hi:[1,0]
	v_max3_f32 v12, v12, |v4|, |v8|
	ds_bpermute_b32 v4, v99, v112
	ds_bpermute_b32 v8, v101, v112
	v_pk_mul_f32 v[2:3], v[32:33], v[2:3] op_sel_hi:[1,0]
	v_max3_f32 v10, v14, |v5|, |v9|
	v_max3_f32 v11, v11, |v6|, |v2|
	v_max3_f32 v13, v13, |v7|, |v3|
	s_waitcnt vmcnt(7) lgkmcnt(1)
	v_pk_mul_f32 v[2:3], v[38:39], v[4:5] op_sel_hi:[1,0]
	s_waitcnt vmcnt(6) lgkmcnt(0)
	v_pk_mul_f32 v[6:7], v[42:43], v[8:9] op_sel_hi:[1,0]
	v_pk_mul_f32 v[4:5], v[36:37], v[4:5] op_sel_hi:[1,0]
	v_max3_f32 v14, v10, |v3|, |v7|
	ds_bpermute_b32 v10, v103, v112
	v_max3_f32 v12, v12, |v2|, |v6|
	ds_bpermute_b32 v2, v105, v112
	v_pk_mul_f32 v[8:9], v[40:41], v[8:9] op_sel_hi:[1,0]
	s_nop 0
	v_max3_f32 v11, v11, |v4|, |v8|
	v_max3_f32 v13, v13, |v5|, |v9|
	s_waitcnt vmcnt(5) lgkmcnt(1)
	v_pk_mul_f32 v[4:5], v[46:47], v[10:11] op_sel_hi:[1,0]
	s_waitcnt vmcnt(4) lgkmcnt(0)
	v_pk_mul_f32 v[8:9], v[50:51], v[2:3] op_sel_hi:[1,0]
	v_pk_mul_f32 v[6:7], v[44:45], v[10:11] op_sel_hi:[1,0]
	v_max3_f32 v12, v12, |v4|, |v8|
	ds_bpermute_b32 v4, v106, v112
	ds_bpermute_b32 v8, v107, v112
	v_pk_mul_f32 v[2:3], v[48:49], v[2:3] op_sel_hi:[1,0]
	v_max3_f32 v10, v14, |v5|, |v9|
	v_max3_f32 v11, v11, |v6|, |v2|
	v_max3_f32 v13, v13, |v7|, |v3|
	s_waitcnt vmcnt(3) lgkmcnt(1)
	v_pk_mul_f32 v[2:3], v[54:55], v[4:5] op_sel_hi:[1,0]
	s_waitcnt vmcnt(2) lgkmcnt(0)
	v_pk_mul_f32 v[6:7], v[58:59], v[8:9] op_sel_hi:[1,0]
	v_pk_mul_f32 v[4:5], v[52:53], v[4:5] op_sel_hi:[1,0]
	v_max3_f32 v14, v10, |v3|, |v7|
	ds_bpermute_b32 v10, v108, v112
	v_max3_f32 v12, v12, |v2|, |v6|
	ds_bpermute_b32 v2, v109, v112
	v_pk_mul_f32 v[8:9], v[56:57], v[8:9] op_sel_hi:[1,0]
	s_nop 0
	v_max3_f32 v11, v11, |v4|, |v8|
	v_max3_f32 v13, v13, |v5|, |v9|
	s_waitcnt vmcnt(1) lgkmcnt(1)
	v_pk_mul_f32 v[4:5], v[62:63], v[10:11] op_sel_hi:[1,0]
	v_pk_mul_f32 v[6:7], v[60:61], v[10:11] op_sel_hi:[1,0]
	s_waitcnt vmcnt(0) lgkmcnt(0)
	v_pk_mul_f32 v[8:9], v[116:117], v[2:3] op_sel_hi:[1,0]
	v_pk_mul_f32 v[2:3], v[114:115], v[2:3] op_sel_hi:[1,0]
	v_max3_f32 v114, v12, |v4|, |v8|
	v_max3_f32 v113, v14, |v5|, |v9|
	v_max3_f32 v115, v11, |v6|, |v2|
	v_max3_f32 v116, v13, |v7|, |v3|
	s_cbranch_scc0 .LBB0_104

; template <int ROT>
; __device__ __forceinline__ void gu_absmax(Frame& F, int s_lo, int s_hi) {
;     ...
;         const float* src = W + (size_t)(512 * kb + 2 * kr) * rowlen + n;
;         int ntl = (ktot - 512 * kb) / 64; ntl = ntl > 8 ? 8 : ntl;
;         f32x4 cm = (f32x4){0.f, 0.f, 0.f, 0.f};
; #pragma unroll 2
;         for (int t = 0; t < ntl; ++t) {
;             const float gv = gain ? gain[512 * kb + 64 * t + lane] : 1.0f;
;             f32x4 v[16];
; #pragma unroll
;             for (int i = 0; i < 16; ++i) v[i] = *(const f32x4*)(src + (size_t)(64 * t + 8 * (i >> 1) + (i & 1)) * rowlen);
.LBB0_102:
	v_lshl_add_u64 v[72:73], v[70:71], 0, s[6:7]
	v_add_co_u32_e32 v2, vcc, 0xa000, v72
	s_waitcnt vmcnt(0)
	ds_bpermute_b32 v104, v83, v74
	v_addc_co_u32_e32 v3, vcc, 0, v73, vcc
	global_load_dwordx4 v[62:65], v[72:73], off nt
	global_load_dwordx4 v[50:53], v[2:3], off offset:3072 nt
	v_add_co_u32_e32 v2, vcc, 0x56000, v72
	ds_bpermute_b32 v102, v85, v74
	s_nop 0
	v_addc_co_u32_e32 v3, vcc, 0, v73, vcc
	v_add_co_u32_e32 v4, vcc, 0x60000, v72
	ds_bpermute_b32 v100, v87, v74
	s_nop 0
	v_addc_co_u32_e32 v5, vcc, 0, v73, vcc
	global_load_dwordx4 v[58:61], v[2:3], off nt
	global_load_dwordx4 v[42:45], v[4:5], off offset:3072 nt
	v_add_co_u32_e32 v2, vcc, 0xac000, v72
	ds_bpermute_b32 v98, v89, v74
	s_nop 0
	v_addc_co_u32_e32 v3, vcc, 0, v73, vcc
	v_add_co_u32_e32 v4, vcc, 0xb6000, v72
	ds_bpermute_b32 v96, v91, v74
	s_nop 0
	v_addc_co_u32_e32 v5, vcc, 0, v73, vcc
	global_load_dwordx4 v[54:57], v[2:3], off nt
	global_load_dwordx4 v[34:37], v[4:5], off offset:3072 nt
	v_add_co_u32_e32 v2, vcc, 0x102000, v72
	ds_bpermute_b32 v94, v93, v74
	s_nop 0
	v_addc_co_u32_e32 v3, vcc, 0, v73, vcc
	v_add_co_u32_e32 v4, vcc, 0x10c000, v72
	ds_bpermute_b32 v92, v95, v74
	s_nop 0
	v_addc_co_u32_e32 v5, vcc, 0, v73, vcc
	global_load_dwordx4 v[46:49], v[2:3], off nt
	global_load_dwordx4 v[26:29], v[4:5], off offset:3072 nt
	v_add_co_u32_e32 v2, vcc, 0x158000, v72
	ds_bpermute_b32 v90, v97, v74
	s_nop 0
	v_addc_co_u32_e32 v3, vcc, 0, v73, vcc
	v_add_co_u32_e32 v4, vcc, 0x162000, v72
	ds_bpermute_b32 v88, v99, v74
	s_nop 0
	v_addc_co_u32_e32 v5, vcc, 0, v73, vcc
	global_load_dwordx4 v[38:41], v[2:3], off nt
	global_load_dwordx4 v[18:21], v[4:5], off offset:3072 nt
	v_add_co_u32_e32 v2, vcc, 0x1ae000, v72
	ds_bpermute_b32 v86, v101, v74
	s_nop 0
	v_addc_co_u32_e32 v3, vcc, 0, v73, vcc
	v_add_co_u32_e32 v4, vcc, 0x1b8000, v72
	ds_bpermute_b32 v84, v103, v74
	s_nop 0
	v_addc_co_u32_e32 v5, vcc, 0, v73, vcc
	global_load_dwordx4 v[30:33], v[2:3], off nt
	global_load_dwordx4 v[10:13], v[4:5], off offset:3072 nt
	v_add_co_u32_e32 v2, vcc, 0x204000, v72
	ds_bpermute_b32 v82, v105, v74
	s_nop 0
	v_addc_co_u32_e32 v3, vcc, 0, v73, vcc
	v_add_co_u32_e32 v4, vcc, 0x20e000, v72
	ds_bpermute_b32 v80, v106, v74
	s_nop 0
	v_addc_co_u32_e32 v5, vcc, 0, v73, vcc
	global_load_dwordx4 v[22:25], v[2:3], off nt
	global_load_dwordx4 v[6:9], v[4:5], off offset:3072 nt
	v_add_co_u32_e32 v2, vcc, 0x25a000, v72
	ds_bpermute_b32 v78, v107, v74
	s_nop 0
	v_addc_co_u32_e32 v3, vcc, 0, v73, vcc
	v_add_co_u32_e32 v4, vcc, 0x264000, v72
	ds_bpermute_b32 v76, v108, v74
	s_nop 0
	v_addc_co_u32_e32 v5, vcc, 0, v73, vcc
	global_load_dwordx4 v[14:17], v[2:3], off nt
	s_nop 0
	global_load_dwordx4 v[2:5], v[4:5], off offset:3072 nt
	ds_bpermute_b32 v74, v109, v74
	s_and_b64 vcc, exec, s[4:5]
	s_cbranch_vccnz .LBB0_99
	global_load_dword v112, v[66:67], off
	s_branch .LBB0_99

; __host__ __device__ __forceinline__ size_t blk_off(int r, int k, int KT) { return ((size_t)((r >> 8) * KT + (k >> 6)) * 256 + (size_t)(r & 255)) * 64 + (size_t)(k & 63); }
; __device__ __forceinline__ unsigned cvt_pk_bf16(float lo, float hi) { unsigned r; asm volatile("v_cvt_pk_bf16_f32 %0, %1, %2" : "=v"(r) : "v"(lo), "v"(hi)); return r; }
; #define FW_Q(f) { if (ROT >= 4) f = bflyq1(f, u1); if (ROT >= 5) f = bflyq2(f, u2); f *= sc; }
; #define FW_Q(f) { if (ROT >= 4) f = bflyq1(f, u1); if (ROT >= 5) f = bflyq2(f, u2); f *= sc; }
; template <int ROT>
; __device__ __forceinline__ void quant_hid_rot(Frame& F, const bf16_t* hidp, unsigned char* hq, float* sh) {
;     ...
;     for (int row = gw; row < M; row += NGW) {
;         const bf16_t* src = hidp + blk_off(row, 64 * kq, KTF) + 8 * c;
;         u32x4 v[22];
; #pragma unroll
;         for (int j = 0; j < 22; ++j) v[j] = *(const u32x4*)(src + (size_t)((j < 21 || lastok) ? 8 * j : 0) * (256 * 64));
;         float am = 0.f;
; #pragma unroll
;         for (int j = 0; j < 22; ++j) {
;             float f0 = __uint_as_float(v[j].x << 16), f1 = __uint_as_float(v[j].x & 0xffff0000u), f2 = __uint_as_float(v[j].y << 16), f3 = __uint_as_float(v[j].y & 0xffff0000u);
;             float f4 = __uint_as_float(v[j].z << 16), f5 = __uint_as_float(v[j].z & 0xffff0000u), f6 = __uint_as_float(v[j].w << 16), f7 = __uint_as_float(v[j].w & 0xffff0000u);
;             if (ROT) {
;     ...
;                 FW_BF(f0, f1) FW_BF(f2, f3) FW_BF(f4, f5) FW_BF(f6, f7)
;                 if (ROT >= 2) { FW_BF(f0, f2) FW_BF(f1, f3) FW_BF(f4, f6) FW_BF(f5, f7) }
;                 if (ROT >= 3) { FW_BF(f0, f4) FW_BF(f1, f5) FW_BF(f2, f6) FW_BF(f3, f7) }
;     ...
;                 const float sc = (ROT == 1 ? 0.70710678118654752f : ROT == 2 ? 0.5f : ROT == 3 ? 0.35355339059327373f : ROT == 4 ? 0.25f : 0.17677669529663687f);
;     ...
;                 FW_Q(f0) FW_Q(f1) FW_Q(f2) FW_Q(f3) FW_Q(f4) FW_Q(f5) FW_Q(f6) FW_Q(f7)
;     ...
;                 u32x4 w; w.x = cvt_pk_bf16(f0, f1); w.y = cvt_pk_bf16(f2, f3); w.z = cvt_pk_bf16(f4, f5); w.w = cvt_pk_bf16(f6, f7);
;                 v[j] = w;
;             }
;             am = fmaxf(fmaxf(am, fmaxf(__builtin_fabsf(f0), __builtin_fabsf(f1))), fmaxf(__builtin_fabsf(f2), __builtin_fabsf(f3)));
;             am = fmaxf(fmaxf(am, fmaxf(__builtin_fabsf(f4), __builtin_fabsf(f5))), fmaxf(__builtin_fabsf(f6), __builtin_fabsf(f7)));
;         }
.LBB0_1311:
	s_ashr_i32 s40, s0, 8
	s_mul_i32 s8, s40, 0xac
	v_add_u32_e32 v2, s8, v1
	v_ashrrev_i32_e32 v3, 31, v2
	s_and_b32 s8, s16, 0x3fc0
	v_lshlrev_b64 v[2:3], 15, v[2:3]
	v_lshl_add_u64 v[2:3], s[84:85], 0, v[2:3]
	s_lshl_b32 s8, s8, 1
	v_lshl_add_u64 v[2:3], v[2:3], 0, s[8:9]
	v_lshl_add_u64 v[2:3], v[2:3], 0, v[74:75]
	v_add_co_u32_e32 v4, vcc, s18, v2
	s_nop 1
	v_addc_co_u32_e32 v5, vcc, 0, v3, vcc
	global_load_dwordx4 v[110:113], v[2:3], off nt
	global_load_dwordx4 v[116:119], v[4:5], off nt
	v_add_co_u32_e32 v4, vcc, s19, v2
	s_waitcnt vmcnt(1)
	v_lshlrev_b32_e32 v114, 16, v110
	v_addc_co_u32_e32 v5, vcc, 0, v3, vcc
	v_add_co_u32_e32 v6, vcc, s20, v2
	v_and_b32_e32 v110, 0xffff0000, v110
	s_nop 0
	v_addc_co_u32_e32 v7, vcc, 0, v3, vcc
	global_load_dwordx4 v[120:123], v[4:5], off nt
	global_load_dwordx4 v[124:127], v[6:7], off nt
	v_add_co_u32_e32 v4, vcc, s21, v2
	v_lshlrev_b32_e32 v115, 16, v111
	s_nop 0
	v_addc_co_u32_e32 v5, vcc, 0, v3, vcc
	v_add_co_u32_e32 v6, vcc, s22, v2
	v_and_b32_e32 v111, 0xffff0000, v111
	s_nop 0
	v_addc_co_u32_e32 v7, vcc, 0, v3, vcc
	global_load_dwordx4 v[70:73], v[4:5], off nt
	global_load_dwordx4 v[66:69], v[6:7], off nt
	v_add_co_u32_e32 v4, vcc, s23, v2
	v_lshlrev_b32_e32 v128, 16, v112
	s_nop 0
	v_addc_co_u32_e32 v5, vcc, 0, v3, vcc
	v_add_co_u32_e32 v6, vcc, s24, v2
	v_and_b32_e32 v112, 0xffff0000, v112
	s_nop 0
	v_addc_co_u32_e32 v7, vcc, 0, v3, vcc
	global_load_dwordx4 v[62:65], v[4:5], off nt
	global_load_dwordx4 v[58:61], v[6:7], off nt
	v_add_co_u32_e32 v4, vcc, s25, v2
	v_lshlrev_b32_e32 v129, 16, v113
	s_nop 0
	v_addc_co_u32_e32 v5, vcc, 0, v3, vcc
	v_add_co_u32_e32 v6, vcc, s26, v2
	v_and_b32_e32 v113, 0xffff0000, v113
	s_nop 0
	v_addc_co_u32_e32 v7, vcc, 0, v3, vcc
	global_load_dwordx4 v[54:57], v[4:5], off nt
	global_load_dwordx4 v[50:53], v[6:7], off nt
	v_add_co_u32_e32 v4, vcc, s27, v2
	v_add_f32_e32 v130, v114, v110
	s_nop 0
	v_addc_co_u32_e32 v5, vcc, 0, v3, vcc
	v_add_co_u32_e32 v6, vcc, s28, v2
	v_sub_f32_e32 v110, v114, v110
	s_nop 0
	v_addc_co_u32_e32 v7, vcc, 0, v3, vcc
	global_load_dwordx4 v[46:49], v[4:5], off nt
	global_load_dwordx4 v[42:45], v[6:7], off nt
	v_add_co_u32_e32 v4, vcc, s29, v2
	v_add_f32_e32 v114, v115, v111
	s_nop 0
	v_addc_co_u32_e32 v5, vcc, 0, v3, vcc
	v_add_co_u32_e32 v6, vcc, s30, v2
	v_sub_f32_e32 v111, v115, v111
	s_nop 0
	v_addc_co_u32_e32 v7, vcc, 0, v3, vcc
	global_load_dwordx4 v[38:41], v[4:5], off nt
	global_load_dwordx4 v[34:37], v[6:7], off nt
	v_add_co_u32_e32 v4, vcc, s31, v2
	v_add_f32_e32 v115, v128, v112
	s_nop 0
	v_addc_co_u32_e32 v5, vcc, 0, v3, vcc
	v_add_co_u32_e32 v6, vcc, s33, v2
	v_sub_f32_e32 v112, v128, v112
	s_nop 0
	v_addc_co_u32_e32 v7, vcc, 0, v3, vcc
	global_load_dwordx4 v[30:33], v[4:5], off nt
	global_load_dwordx4 v[26:29], v[6:7], off nt
	v_add_co_u32_e32 v4, vcc, s34, v2
	v_add_f32_e32 v128, v129, v113
	s_nop 0
	v_addc_co_u32_e32 v5, vcc, 0, v3, vcc
	v_add_co_u32_e32 v6, vcc, s35, v2
	v_sub_f32_e32 v113, v129, v113
	s_nop 0
	v_addc_co_u32_e32 v7, vcc, 0, v3, vcc
	global_load_dwordx4 v[22:25], v[4:5], off nt
	global_load_dwordx4 v[18:21], v[6:7], off nt
	v_add_co_u32_e32 v4, vcc, s36, v2
	v_add_f32_e32 v129, v130, v114
	s_nop 0
	v_addc_co_u32_e32 v5, vcc, 0, v3, vcc
	v_add_co_u32_e32 v6, vcc, s37, v2
	v_sub_f32_e32 v114, v130, v114
	s_nop 0
	v_addc_co_u32_e32 v7, vcc, 0, v3, vcc
	global_load_dwordx4 v[14:17], v[4:5], off nt
	global_load_dwordx4 v[10:13], v[6:7], off nt
	v_add_co_u32_e32 v4, vcc, s38, v2
	v_add_f32_e32 v130, v110, v111
	v_sub_f32_e32 v110, v110, v111
	v_addc_co_u32_e32 v5, vcc, 0, v3, vcc
	v_lshl_add_u64 v[2:3], v[2:3], 0, v[78:79]
	v_add_f32_e32 v111, v115, v128
	v_sub_f32_e32 v115, v115, v128
	v_add_f32_e32 v128, v112, v113
	v_sub_f32_e32 v112, v112, v113
	v_mul_f32_e32 v113, 0.5, v129
	v_mul_f32_e32 v129, 0.5, v130
	v_mul_f32_e32 v130, 0.5, v114
	v_mul_f32_e32 v131, 0.5, v110
	global_load_dwordx4 v[6:9], v[4:5], off nt
	s_nop 0
	global_load_dwordx4 v[2:5], v[2:3], off nt
	v_mul_f32_e32 v132, 0.5, v111
	v_mul_f32_e32 v128, 0.5, v128
	v_mul_f32_e32 v133, 0.5, v115
	v_mul_f32_e32 v112, 0.5, v112
	v_cvt_pk_bf16_f32 v115, v113, v129
	v_max_f32_e64 v113, |v113|, |v129|
	v_max_f32_e64 v129, |v130|, |v131|
	v_cvt_pk_bf16_f32 v114, v130, v131
	v_cvt_pk_bf16_f32 v111, v132, v128
	v_cvt_pk_bf16_f32 v110, v133, v112
	v_max3_f32 v113, v113, 0, v129
	v_max_f32_e64 v128, |v132|, |v128|
	v_max_f32_e64 v112, |v133|, |v112|
	v_max3_f32 v128, v113, v128, v112
	s_waitcnt vmcnt(20)
	v_lshlrev_b32_e32 v112, 16, v116
	v_and_b32_e32 v113, 0xffff0000, v116
	v_lshlrev_b32_e32 v116, 16, v117
	v_and_b32_e32 v117, 0xffff0000, v117
	v_lshlrev_b32_e32 v129, 16, v118
	v_and_b32_e32 v118, 0xffff0000, v118
	v_lshlrev_b32_e32 v130, 16, v119
	v_and_b32_e32 v119, 0xffff0000, v119
	v_add_f32_e32 v131, v112, v113
	v_sub_f32_e32 v112, v112, v113
	v_add_f32_e32 v113, v116, v117
	v_sub_f32_e32 v116, v116, v117
	v_add_f32_e32 v117, v129, v118
	v_sub_f32_e32 v118, v129, v118
	v_add_f32_e32 v129, v130, v119
	v_sub_f32_e32 v119, v130, v119
	v_add_f32_e32 v130, v131, v113
	v_sub_f32_e32 v113, v131, v113
	v_add_f32_e32 v131, v112, v116
	v_sub_f32_e32 v112, v112, v116
	v_add_f32_e32 v116, v117, v129
	v_sub_f32_e32 v117, v117, v129
	v_add_f32_e32 v129, v118, v119
	v_sub_f32_e32 v118, v118, v119
	v_mul_f32_e32 v130, 0.5, v130
	v_mul_f32_e32 v131, 0.5, v131
	v_mul_f32_e32 v132, 0.5, v113
	v_mul_f32_e32 v133, 0.5, v112
	v_mul_f32_e32 v116, 0.5, v116
	v_mul_f32_e32 v129, 0.5, v129
	v_mul_f32_e32 v117, 0.5, v117
	v_mul_f32_e32 v134, 0.5, v118
	v_cvt_pk_bf16_f32 v119, v130, v131
	v_max_f32_e64 v130, |v130|, |v131|
	v_max_f32_e64 v131, |v132|, |v133|
	v_cvt_pk_bf16_f32 v118, v132, v133
	v_cvt_pk_bf16_f32 v113, v116, v129
	v_cvt_pk_bf16_f32 v112, v117, v134
	v_max3_f32 v128, v128, v130, v131
	v_max_f32_e64 v116, |v116|, |v129|
	v_max_f32_e64 v117, |v117|, |v134|
	v_max3_f32 v128, v128, v116, v117
	s_waitcnt vmcnt(19)
; __device__ __forceinline__ unsigned cvt_pk_bf16(float lo, float hi) { unsigned r; asm volatile("v_cvt_pk_bf16_f32 %0, %1, %2" : "=v"(r) : "v"(lo), "v"(hi)); return r; }
; #define FW_Q(f) { if (ROT >= 4) f = bflyq1(f, u1); if (ROT >= 5) f = bflyq2(f, u2); f *= sc; }
; #define FW_Q(f) { if (ROT >= 4) f = bflyq1(f, u1); if (ROT >= 5) f = bflyq2(f, u2); f *= sc; }
; template <int ROT>
; __device__ __forceinline__ void quant_hid_rot(Frame& F, const bf16_t* hidp, unsigned char* hq, float* sh) {
;     ...
; #pragma unroll
;         for (int j = 0; j < 22; ++j) {
;             float f0 = __uint_as_float(v[j].x << 16), f1 = __uint_as_float(v[j].x & 0xffff0000u), f2 = __uint_as_float(v[j].y << 16), f3 = __uint_as_float(v[j].y & 0xffff0000u);
;             float f4 = __uint_as_float(v[j].z << 16), f5 = __uint_as_float(v[j].z & 0xffff0000u), f6 = __uint_as_float(v[j].w << 16), f7 = __uint_as_float(v[j].w & 0xffff0000u);
;             if (ROT) {
;     ...
;                 FW_BF(f0, f1) FW_BF(f2, f3) FW_BF(f4, f5) FW_BF(f6, f7)
;                 if (ROT >= 2) { FW_BF(f0, f2) FW_BF(f1, f3) FW_BF(f4, f6) FW_BF(f5, f7) }
;                 if (ROT >= 3) { FW_BF(f0, f4) FW_BF(f1, f5) FW_BF(f2, f6) FW_BF(f3, f7) }
;     ...
;                 const float sc = (ROT == 1 ? 0.70710678118654752f : ROT == 2 ? 0.5f : ROT == 3 ? 0.35355339059327373f : ROT == 4 ? 0.25f : 0.17677669529663687f);
;     ...
;                 FW_Q(f0) FW_Q(f1) FW_Q(f2) FW_Q(f3) FW_Q(f4) FW_Q(f5) FW_Q(f6) FW_Q(f7)
;     ...
;                 u32x4 w; w.x = cvt_pk_bf16(f0, f1); w.y = cvt_pk_bf16(f2, f3); w.z = cvt_pk_bf16(f4, f5); w.w = cvt_pk_bf16(f6, f7);
;                 v[j] = w;
;             }
;             am = fmaxf(fmaxf(am, fmaxf(__builtin_fabsf(f0), __builtin_fabsf(f1))), fmaxf(__builtin_fabsf(f2), __builtin_fabsf(f3)));
;             am = fmaxf(fmaxf(am, fmaxf(__builtin_fabsf(f4), __builtin_fabsf(f5))), fmaxf(__builtin_fabsf(f6), __builtin_fabsf(f7)));
;         }
	v_lshlrev_b32_e32 v116, 16, v120
	v_and_b32_e32 v117, 0xffff0000, v120
	v_lshlrev_b32_e32 v120, 16, v121
	v_and_b32_e32 v121, 0xffff0000, v121
	v_lshlrev_b32_e32 v129, 16, v122
	v_and_b32_e32 v122, 0xffff0000, v122
	v_lshlrev_b32_e32 v130, 16, v123
	v_and_b32_e32 v123, 0xffff0000, v123
	v_add_f32_e32 v131, v116, v117
	v_sub_f32_e32 v116, v116, v117
	v_add_f32_e32 v117, v120, v121
	v_sub_f32_e32 v120, v120, v121
	v_add_f32_e32 v121, v129, v122
	v_sub_f32_e32 v122, v129, v122
	v_add_f32_e32 v129, v130, v123
	v_sub_f32_e32 v123, v130, v123
	v_add_f32_e32 v130, v131, v117
	v_sub_f32_e32 v117, v131, v117
	v_add_f32_e32 v131, v116, v120
	v_sub_f32_e32 v116, v116, v120
	v_add_f32_e32 v120, v121, v129
	v_sub_f32_e32 v121, v121, v129
	v_add_f32_e32 v129, v122, v123
	v_sub_f32_e32 v122, v122, v123
	v_mul_f32_e32 v130, 0.5, v130
	v_mul_f32_e32 v131, 0.5, v131
	v_mul_f32_e32 v132, 0.5, v117
	v_mul_f32_e32 v133, 0.5, v116
	v_mul_f32_e32 v120, 0.5, v120
	v_mul_f32_e32 v129, 0.5, v129
	v_mul_f32_e32 v121, 0.5, v121
	v_mul_f32_e32 v134, 0.5, v122
	v_cvt_pk_bf16_f32 v123, v130, v131
	v_max_f32_e64 v130, |v130|, |v131|
	v_max_f32_e64 v131, |v132|, |v133|
	v_cvt_pk_bf16_f32 v122, v132, v133
	v_cvt_pk_bf16_f32 v117, v120, v129
	v_cvt_pk_bf16_f32 v116, v121, v134
	v_max3_f32 v128, v128, v130, v131
	v_max_f32_e64 v120, |v120|, |v129|
	v_max_f32_e64 v121, |v121|, |v134|
	v_max3_f32 v128, v128, v120, v121
	s_waitcnt vmcnt(18)
	v_lshlrev_b32_e32 v120, 16, v124
	v_and_b32_e32 v121, 0xffff0000, v124
	v_lshlrev_b32_e32 v124, 16, v125
	v_and_b32_e32 v125, 0xffff0000, v125
	v_lshlrev_b32_e32 v129, 16, v126
	v_and_b32_e32 v126, 0xffff0000, v126
	v_lshlrev_b32_e32 v130, 16, v127
	v_and_b32_e32 v127, 0xffff0000, v127
	v_add_f32_e32 v131, v120, v121
	v_sub_f32_e32 v120, v120, v121
	v_add_f32_e32 v121, v124, v125
	v_sub_f32_e32 v124, v124, v125
	v_add_f32_e32 v125, v129, v126
	v_sub_f32_e32 v126, v129, v126
	v_add_f32_e32 v129, v130, v127
	v_sub_f32_e32 v127, v130, v127
	v_add_f32_e32 v130, v131, v121
	v_sub_f32_e32 v121, v131, v121
	v_add_f32_e32 v131, v120, v124
	v_sub_f32_e32 v120, v120, v124
	v_add_f32_e32 v124, v125, v129
	v_sub_f32_e32 v125, v125, v129
	v_add_f32_e32 v129, v126, v127
	v_sub_f32_e32 v126, v126, v127
	v_mul_f32_e32 v127, 0.5, v130
	v_mul_f32_e32 v130, 0.5, v131
	v_mul_f32_e32 v131, 0.5, v121
	v_mul_f32_e32 v132, 0.5, v120
	v_mul_f32_e32 v133, 0.5, v124
	v_mul_f32_e32 v129, 0.5, v129
	v_mul_f32_e32 v134, 0.5, v125
	v_mul_f32_e32 v126, 0.5, v126
	v_cvt_pk_bf16_f32 v125, v127, v130
	v_max_f32_e64 v127, |v127|, |v130|
	v_max_f32_e64 v130, |v131|, |v132|
	v_cvt_pk_bf16_f32 v124, v131, v132
	v_cvt_pk_bf16_f32 v121, v133, v129
	v_cvt_pk_bf16_f32 v120, v134, v126
	v_max3_f32 v127, v128, v127, v130
	v_max_f32_e64 v128, |v133|, |v129|
	v_max_f32_e64 v126, |v134|, |v126|
	v_max3_f32 v126, v127, v128, v126
	s_waitcnt vmcnt(17)
	v_lshlrev_b32_e32 v127, 16, v70
	v_and_b32_e32 v70, 0xffff0000, v70
	v_lshlrev_b32_e32 v128, 16, v71
	v_and_b32_e32 v71, 0xffff0000, v71
	v_lshlrev_b32_e32 v129, 16, v72
	v_and_b32_e32 v72, 0xffff0000, v72
	v_lshlrev_b32_e32 v130, 16, v73
	v_and_b32_e32 v73, 0xffff0000, v73
	v_add_f32_e32 v131, v127, v70
	v_sub_f32_e32 v70, v127, v70
	v_add_f32_e32 v127, v128, v71
	v_sub_f32_e32 v71, v128, v71
	v_add_f32_e32 v128, v129, v72
	v_sub_f32_e32 v72, v129, v72
	v_add_f32_e32 v129, v130, v73
	v_sub_f32_e32 v73, v130, v73
	v_add_f32_e32 v130, v131, v127
	v_sub_f32_e32 v127, v131, v127
	v_add_f32_e32 v131, v70, v71
	v_sub_f32_e32 v70, v70, v71
	v_add_f32_e32 v71, v128, v129
	v_sub_f32_e32 v128, v128, v129
	v_add_f32_e32 v129, v72, v73
	v_sub_f32_e32 v72, v72, v73
	v_mul_f32_e32 v130, 0.5, v130
	v_mul_f32_e32 v131, 0.5, v131
	v_mul_f32_e32 v127, 0.5, v127
	v_mul_f32_e32 v132, 0.5, v70
	v_mul_f32_e32 v133, 0.5, v71
	v_mul_f32_e32 v129, 0.5, v129
	v_mul_f32_e32 v128, 0.5, v128
	v_mul_f32_e32 v134, 0.5, v72
	v_cvt_pk_bf16_f32 v73, v130, v131
	v_cvt_pk_bf16_f32 v72, v127, v132
	v_max_f32_e64 v130, |v130|, |v131|
	v_max_f32_e64 v127, |v127|, |v132|
	v_cvt_pk_bf16_f32 v71, v133, v129
	v_cvt_pk_bf16_f32 v70, v128, v134
	v_max3_f32 v126, v126, v130, v127
	v_max_f32_e64 v127, |v133|, |v129|
	v_max_f32_e64 v128, |v128|, |v134|
	v_max3_f32 v126, v126, v127, v128
	s_waitcnt vmcnt(16)
	v_lshlrev_b32_e32 v127, 16, v66
	v_and_b32_e32 v66, 0xffff0000, v66
	v_lshlrev_b32_e32 v128, 16, v67
	v_and_b32_e32 v67, 0xffff0000, v67
	v_lshlrev_b32_e32 v129, 16, v68
	v_and_b32_e32 v68, 0xffff0000, v68
	v_lshlrev_b32_e32 v130, 16, v69
	v_and_b32_e32 v69, 0xffff0000, v69
	v_add_f32_e32 v131, v127, v66
	v_sub_f32_e32 v66, v127, v66
	v_add_f32_e32 v127, v128, v67
	v_sub_f32_e32 v67, v128, v67
	v_add_f32_e32 v128, v129, v68
	v_sub_f32_e32 v68, v129, v68
	v_add_f32_e32 v129, v130, v69
	v_sub_f32_e32 v69, v130, v69
	v_add_f32_e32 v130, v131, v127
	v_sub_f32_e32 v127, v131, v127
	v_add_f32_e32 v131, v66, v67
	v_sub_f32_e32 v66, v66, v67
	v_add_f32_e32 v67, v128, v129
	v_sub_f32_e32 v128, v128, v129
	v_add_f32_e32 v129, v68, v69
	v_sub_f32_e32 v68, v68, v69
	v_mul_f32_e32 v130, 0.5, v130
	v_mul_f32_e32 v131, 0.5, v131
	v_mul_f32_e32 v127, 0.5, v127
	v_mul_f32_e32 v132, 0.5, v66
	v_mul_f32_e32 v133, 0.5, v67
	v_mul_f32_e32 v129, 0.5, v129
	v_mul_f32_e32 v128, 0.5, v128
	v_mul_f32_e32 v134, 0.5, v68
	v_cvt_pk_bf16_f32 v69, v130, v131
	v_cvt_pk_bf16_f32 v68, v127, v132
	v_max_f32_e64 v130, |v130|, |v131|
	v_max_f32_e64 v127, |v127|, |v132|
	v_cvt_pk_bf16_f32 v67, v133, v129
	v_cvt_pk_bf16_f32 v66, v128, v134
	v_max3_f32 v126, v126, v130, v127
	v_max_f32_e64 v127, |v133|, |v129|
	v_max_f32_e64 v128, |v128|, |v134|
	v_max3_f32 v126, v126, v127, v128
	s_waitcnt vmcnt(15)
; __device__ __forceinline__ unsigned cvt_pk_bf16(float lo, float hi) { unsigned r; asm volatile("v_cvt_pk_bf16_f32 %0, %1, %2" : "=v"(r) : "v"(lo), "v"(hi)); return r; }
; #define FW_Q(f) { if (ROT >= 4) f = bflyq1(f, u1); if (ROT >= 5) f = bflyq2(f, u2); f *= sc; }
; #define FW_Q(f) { if (ROT >= 4) f = bflyq1(f, u1); if (ROT >= 5) f = bflyq2(f, u2); f *= sc; }
; template <int ROT>
; __device__ __forceinline__ void quant_hid_rot(Frame& F, const bf16_t* hidp, unsigned char* hq, float* sh) {
;     ...
; #pragma unroll
;         for (int j = 0; j < 22; ++j) {
;             float f0 = __uint_as_float(v[j].x << 16), f1 = __uint_as_float(v[j].x & 0xffff0000u), f2 = __uint_as_float(v[j].y << 16), f3 = __uint_as_float(v[j].y & 0xffff0000u);
;             float f4 = __uint_as_float(v[j].z << 16), f5 = __uint_as_float(v[j].z & 0xffff0000u), f6 = __uint_as_float(v[j].w << 16), f7 = __uint_as_float(v[j].w & 0xffff0000u);
;             if (ROT) {
;     ...
;                 FW_BF(f0, f1) FW_BF(f2, f3) FW_BF(f4, f5) FW_BF(f6, f7)
;                 if (ROT >= 2) { FW_BF(f0, f2) FW_BF(f1, f3) FW_BF(f4, f6) FW_BF(f5, f7) }
;                 if (ROT >= 3) { FW_BF(f0, f4) FW_BF(f1, f5) FW_BF(f2, f6) FW_BF(f3, f7) }
;     ...
;                 const float sc = (ROT == 1 ? 0.70710678118654752f : ROT == 2 ? 0.5f : ROT == 3 ? 0.35355339059327373f : ROT == 4 ? 0.25f : 0.17677669529663687f);
;     ...
;                 FW_Q(f0) FW_Q(f1) FW_Q(f2) FW_Q(f3) FW_Q(f4) FW_Q(f5) FW_Q(f6) FW_Q(f7)
;     ...
;                 u32x4 w; w.x = cvt_pk_bf16(f0, f1); w.y = cvt_pk_bf16(f2, f3); w.z = cvt_pk_bf16(f4, f5); w.w = cvt_pk_bf16(f6, f7);
;                 v[j] = w;
;             }
;             am = fmaxf(fmaxf(am, fmaxf(__builtin_fabsf(f0), __builtin_fabsf(f1))), fmaxf(__builtin_fabsf(f2), __builtin_fabsf(f3)));
;             am = fmaxf(fmaxf(am, fmaxf(__builtin_fabsf(f4), __builtin_fabsf(f5))), fmaxf(__builtin_fabsf(f6), __builtin_fabsf(f7)));
;         }
	v_lshlrev_b32_e32 v127, 16, v62
	v_and_b32_e32 v62, 0xffff0000, v62
	v_lshlrev_b32_e32 v128, 16, v63
	v_and_b32_e32 v63, 0xffff0000, v63
	v_lshlrev_b32_e32 v129, 16, v64
	v_and_b32_e32 v64, 0xffff0000, v64
	v_lshlrev_b32_e32 v130, 16, v65
	v_and_b32_e32 v65, 0xffff0000, v65
	v_add_f32_e32 v131, v127, v62
	v_sub_f32_e32 v62, v127, v62
	v_add_f32_e32 v127, v128, v63
	v_sub_f32_e32 v63, v128, v63
	v_add_f32_e32 v128, v129, v64
	v_sub_f32_e32 v64, v129, v64
	v_add_f32_e32 v129, v130, v65
	v_sub_f32_e32 v65, v130, v65
	v_add_f32_e32 v130, v131, v127
	v_sub_f32_e32 v127, v131, v127
	v_add_f32_e32 v131, v62, v63
	v_sub_f32_e32 v62, v62, v63
	v_add_f32_e32 v63, v128, v129
	v_sub_f32_e32 v128, v128, v129
	v_add_f32_e32 v129, v64, v65
	v_sub_f32_e32 v64, v64, v65
	v_mul_f32_e32 v130, 0.5, v130
	v_mul_f32_e32 v131, 0.5, v131
	v_mul_f32_e32 v127, 0.5, v127
	v_mul_f32_e32 v132, 0.5, v62
	v_mul_f32_e32 v133, 0.5, v63
	v_mul_f32_e32 v129, 0.5, v129
	v_mul_f32_e32 v128, 0.5, v128
	v_mul_f32_e32 v134, 0.5, v64
	v_cvt_pk_bf16_f32 v65, v130, v131
	v_cvt_pk_bf16_f32 v64, v127, v132
	v_max_f32_e64 v130, |v130|, |v131|
	v_max_f32_e64 v127, |v127|, |v132|
	v_cvt_pk_bf16_f32 v63, v133, v129
	v_cvt_pk_bf16_f32 v62, v128, v134
	v_max3_f32 v126, v126, v130, v127
	v_max_f32_e64 v127, |v133|, |v129|
	v_max_f32_e64 v128, |v128|, |v134|
	v_max3_f32 v126, v126, v127, v128
	s_waitcnt vmcnt(14)
	v_lshlrev_b32_e32 v127, 16, v58
	v_and_b32_e32 v58, 0xffff0000, v58
	v_lshlrev_b32_e32 v128, 16, v59
	v_and_b32_e32 v59, 0xffff0000, v59
	v_lshlrev_b32_e32 v129, 16, v60
	v_and_b32_e32 v60, 0xffff0000, v60
	v_lshlrev_b32_e32 v130, 16, v61
	v_and_b32_e32 v61, 0xffff0000, v61
	v_add_f32_e32 v131, v127, v58
	v_sub_f32_e32 v58, v127, v58
	v_add_f32_e32 v127, v128, v59
	v_sub_f32_e32 v59, v128, v59
	v_add_f32_e32 v128, v129, v60
	v_sub_f32_e32 v60, v129, v60
	v_add_f32_e32 v129, v130, v61
	v_sub_f32_e32 v61, v130, v61
	v_add_f32_e32 v130, v131, v127
	v_sub_f32_e32 v127, v131, v127
	v_add_f32_e32 v131, v58, v59
	v_sub_f32_e32 v58, v58, v59
	v_add_f32_e32 v59, v128, v129
	v_sub_f32_e32 v128, v128, v129
	v_add_f32_e32 v129, v60, v61
	v_sub_f32_e32 v60, v60, v61
	v_mul_f32_e32 v130, 0.5, v130
	v_mul_f32_e32 v131, 0.5, v131
	v_mul_f32_e32 v127, 0.5, v127
	v_mul_f32_e32 v132, 0.5, v58
	v_mul_f32_e32 v133, 0.5, v59
	v_mul_f32_e32 v129, 0.5, v129
	v_mul_f32_e32 v128, 0.5, v128
	v_mul_f32_e32 v134, 0.5, v60
	v_cvt_pk_bf16_f32 v61, v130, v131
	v_cvt_pk_bf16_f32 v60, v127, v132
	v_max_f32_e64 v130, |v130|, |v131|
	v_max_f32_e64 v127, |v127|, |v132|
	v_cvt_pk_bf16_f32 v59, v133, v129
	v_cvt_pk_bf16_f32 v58, v128, v134
	v_max3_f32 v126, v126, v130, v127
	v_max_f32_e64 v127, |v133|, |v129|
	v_max_f32_e64 v128, |v128|, |v134|
	v_max3_f32 v126, v126, v127, v128
	s_waitcnt vmcnt(13)
	v_lshlrev_b32_e32 v127, 16, v54
	v_and_b32_e32 v54, 0xffff0000, v54
	v_lshlrev_b32_e32 v128, 16, v55
	v_and_b32_e32 v55, 0xffff0000, v55
	v_lshlrev_b32_e32 v129, 16, v56
	v_and_b32_e32 v56, 0xffff0000, v56
	v_lshlrev_b32_e32 v130, 16, v57
	v_and_b32_e32 v57, 0xffff0000, v57
	v_add_f32_e32 v131, v127, v54
	v_sub_f32_e32 v54, v127, v54
	v_add_f32_e32 v127, v128, v55
	v_sub_f32_e32 v55, v128, v55
	v_add_f32_e32 v128, v129, v56
	v_sub_f32_e32 v56, v129, v56
	v_add_f32_e32 v129, v130, v57
	v_sub_f32_e32 v57, v130, v57
	v_add_f32_e32 v130, v131, v127
	v_sub_f32_e32 v127, v131, v127
	v_add_f32_e32 v131, v54, v55
	v_sub_f32_e32 v54, v54, v55
	v_add_f32_e32 v55, v128, v129
	v_sub_f32_e32 v128, v128, v129
	v_add_f32_e32 v129, v56, v57
	v_sub_f32_e32 v56, v56, v57
	v_mul_f32_e32 v130, 0.5, v130
	v_mul_f32_e32 v131, 0.5, v131
	v_mul_f32_e32 v127, 0.5, v127
	v_mul_f32_e32 v132, 0.5, v54
	v_mul_f32_e32 v133, 0.5, v55
	v_mul_f32_e32 v129, 0.5, v129
	v_mul_f32_e32 v128, 0.5, v128
	v_mul_f32_e32 v134, 0.5, v56
	v_cvt_pk_bf16_f32 v57, v130, v131
	v_cvt_pk_bf16_f32 v56, v127, v132
	v_max_f32_e64 v130, |v130|, |v131|
	v_max_f32_e64 v127, |v127|, |v132|
	v_cvt_pk_bf16_f32 v55, v133, v129
	v_cvt_pk_bf16_f32 v54, v128, v134
	v_max3_f32 v126, v126, v130, v127
	v_max_f32_e64 v127, |v133|, |v129|
	v_max_f32_e64 v128, |v128|, |v134|
	v_max3_f32 v126, v126, v127, v128
	s_waitcnt vmcnt(12)
	v_lshlrev_b32_e32 v127, 16, v50
	v_and_b32_e32 v50, 0xffff0000, v50
	v_lshlrev_b32_e32 v128, 16, v51
	v_and_b32_e32 v51, 0xffff0000, v51
	v_lshlrev_b32_e32 v129, 16, v52
	v_and_b32_e32 v52, 0xffff0000, v52
	v_lshlrev_b32_e32 v130, 16, v53
	v_and_b32_e32 v53, 0xffff0000, v53
	v_add_f32_e32 v131, v127, v50
	v_sub_f32_e32 v50, v127, v50
	v_add_f32_e32 v127, v128, v51
	v_sub_f32_e32 v51, v128, v51
	v_add_f32_e32 v128, v129, v52
	v_sub_f32_e32 v52, v129, v52
	v_add_f32_e32 v129, v130, v53
	v_sub_f32_e32 v53, v130, v53
	v_add_f32_e32 v130, v131, v127
	v_sub_f32_e32 v127, v131, v127
	v_add_f32_e32 v131, v50, v51
	v_sub_f32_e32 v50, v50, v51
	v_add_f32_e32 v51, v128, v129
	v_sub_f32_e32 v128, v128, v129
	v_add_f32_e32 v129, v52, v53
	v_sub_f32_e32 v52, v52, v53
	v_mul_f32_e32 v130, 0.5, v130
	v_mul_f32_e32 v131, 0.5, v131
	v_mul_f32_e32 v127, 0.5, v127
	v_mul_f32_e32 v132, 0.5, v50
	v_mul_f32_e32 v133, 0.5, v51
	v_mul_f32_e32 v129, 0.5, v129
	v_mul_f32_e32 v128, 0.5, v128
	v_mul_f32_e32 v134, 0.5, v52
	v_cvt_pk_bf16_f32 v53, v130, v131
	v_cvt_pk_bf16_f32 v52, v127, v132
	v_max_f32_e64 v130, |v130|, |v131|
	v_max_f32_e64 v127, |v127|, |v132|
	v_cvt_pk_bf16_f32 v51, v133, v129
	v_cvt_pk_bf16_f32 v50, v128, v134
	v_max3_f32 v126, v126, v130, v127
	v_max_f32_e64 v127, |v133|, |v129|
	v_max_f32_e64 v128, |v128|, |v134|
	v_max3_f32 v126, v126, v127, v128
	s_waitcnt vmcnt(11)
; __device__ __forceinline__ unsigned cvt_pk_bf16(float lo, float hi) { unsigned r; asm volatile("v_cvt_pk_bf16_f32 %0, %1, %2" : "=v"(r) : "v"(lo), "v"(hi)); return r; }
; #define FW_Q(f) { if (ROT >= 4) f = bflyq1(f, u1); if (ROT >= 5) f = bflyq2(f, u2); f *= sc; }
; #define FW_Q(f) { if (ROT >= 4) f = bflyq1(f, u1); if (ROT >= 5) f = bflyq2(f, u2); f *= sc; }
; template <int ROT>
; __device__ __forceinline__ void quant_hid_rot(Frame& F, const bf16_t* hidp, unsigned char* hq, float* sh) {
;     ...
; #pragma unroll
;         for (int j = 0; j < 22; ++j) {
;             float f0 = __uint_as_float(v[j].x << 16), f1 = __uint_as_float(v[j].x & 0xffff0000u), f2 = __uint_as_float(v[j].y << 16), f3 = __uint_as_float(v[j].y & 0xffff0000u);
;             float f4 = __uint_as_float(v[j].z << 16), f5 = __uint_as_float(v[j].z & 0xffff0000u), f6 = __uint_as_float(v[j].w << 16), f7 = __uint_as_float(v[j].w & 0xffff0000u);
;             if (ROT) {
;     ...
;                 FW_BF(f0, f1) FW_BF(f2, f3) FW_BF(f4, f5) FW_BF(f6, f7)
;                 if (ROT >= 2) { FW_BF(f0, f2) FW_BF(f1, f3) FW_BF(f4, f6) FW_BF(f5, f7) }
;                 if (ROT >= 3) { FW_BF(f0, f4) FW_BF(f1, f5) FW_BF(f2, f6) FW_BF(f3, f7) }
;     ...
;                 const float sc = (ROT == 1 ? 0.70710678118654752f : ROT == 2 ? 0.5f : ROT == 3 ? 0.35355339059327373f : ROT == 4 ? 0.25f : 0.17677669529663687f);
;     ...
;                 FW_Q(f0) FW_Q(f1) FW_Q(f2) FW_Q(f3) FW_Q(f4) FW_Q(f5) FW_Q(f6) FW_Q(f7)
;     ...
;                 u32x4 w; w.x = cvt_pk_bf16(f0, f1); w.y = cvt_pk_bf16(f2, f3); w.z = cvt_pk_bf16(f4, f5); w.w = cvt_pk_bf16(f6, f7);
;                 v[j] = w;
;             }
;             am = fmaxf(fmaxf(am, fmaxf(__builtin_fabsf(f0), __builtin_fabsf(f1))), fmaxf(__builtin_fabsf(f2), __builtin_fabsf(f3)));
;             am = fmaxf(fmaxf(am, fmaxf(__builtin_fabsf(f4), __builtin_fabsf(f5))), fmaxf(__builtin_fabsf(f6), __builtin_fabsf(f7)));
;         }
	v_lshlrev_b32_e32 v127, 16, v46
	v_and_b32_e32 v46, 0xffff0000, v46
	v_lshlrev_b32_e32 v128, 16, v47
	v_and_b32_e32 v47, 0xffff0000, v47
	v_lshlrev_b32_e32 v129, 16, v48
	v_and_b32_e32 v48, 0xffff0000, v48
	v_lshlrev_b32_e32 v130, 16, v49
	v_and_b32_e32 v49, 0xffff0000, v49
	v_add_f32_e32 v131, v127, v46
	v_sub_f32_e32 v46, v127, v46
	v_add_f32_e32 v127, v128, v47
	v_sub_f32_e32 v47, v128, v47
	v_add_f32_e32 v128, v129, v48
	v_sub_f32_e32 v48, v129, v48
	v_add_f32_e32 v129, v130, v49
	v_sub_f32_e32 v49, v130, v49
	v_add_f32_e32 v130, v131, v127
	v_sub_f32_e32 v127, v131, v127
	v_add_f32_e32 v131, v46, v47
	v_sub_f32_e32 v46, v46, v47
	v_add_f32_e32 v47, v128, v129
	v_sub_f32_e32 v128, v128, v129
	v_add_f32_e32 v129, v48, v49
	v_sub_f32_e32 v48, v48, v49
	v_mul_f32_e32 v130, 0.5, v130
	v_mul_f32_e32 v131, 0.5, v131
	v_mul_f32_e32 v127, 0.5, v127
	v_mul_f32_e32 v132, 0.5, v46
	v_mul_f32_e32 v133, 0.5, v47
	v_mul_f32_e32 v129, 0.5, v129
	v_mul_f32_e32 v128, 0.5, v128
	v_mul_f32_e32 v134, 0.5, v48
	v_cvt_pk_bf16_f32 v49, v130, v131
	v_cvt_pk_bf16_f32 v48, v127, v132
	v_max_f32_e64 v130, |v130|, |v131|
	v_max_f32_e64 v127, |v127|, |v132|
	v_cvt_pk_bf16_f32 v47, v133, v129
	v_cvt_pk_bf16_f32 v46, v128, v134
	v_max3_f32 v126, v126, v130, v127
	v_max_f32_e64 v127, |v133|, |v129|
	v_max_f32_e64 v128, |v128|, |v134|
	v_max3_f32 v126, v126, v127, v128
	s_waitcnt vmcnt(10)
	v_lshlrev_b32_e32 v127, 16, v42
	v_and_b32_e32 v42, 0xffff0000, v42
	v_lshlrev_b32_e32 v128, 16, v43
	v_and_b32_e32 v43, 0xffff0000, v43
	v_lshlrev_b32_e32 v129, 16, v44
	v_and_b32_e32 v44, 0xffff0000, v44
	v_lshlrev_b32_e32 v130, 16, v45
	v_and_b32_e32 v45, 0xffff0000, v45
	v_add_f32_e32 v131, v127, v42
	v_sub_f32_e32 v42, v127, v42
	v_add_f32_e32 v127, v128, v43
	v_sub_f32_e32 v43, v128, v43
	v_add_f32_e32 v128, v129, v44
	v_sub_f32_e32 v44, v129, v44
	v_add_f32_e32 v129, v130, v45
	v_sub_f32_e32 v45, v130, v45
	v_add_f32_e32 v130, v131, v127
	v_sub_f32_e32 v127, v131, v127
	v_add_f32_e32 v131, v42, v43
	v_sub_f32_e32 v42, v42, v43
	v_add_f32_e32 v43, v128, v129
	v_sub_f32_e32 v128, v128, v129
	v_add_f32_e32 v129, v44, v45
	v_sub_f32_e32 v44, v44, v45
	v_mul_f32_e32 v130, 0.5, v130
	v_mul_f32_e32 v131, 0.5, v131
	v_mul_f32_e32 v127, 0.5, v127
	v_mul_f32_e32 v132, 0.5, v42
	v_mul_f32_e32 v133, 0.5, v43
	v_mul_f32_e32 v129, 0.5, v129
	v_mul_f32_e32 v128, 0.5, v128
	v_mul_f32_e32 v134, 0.5, v44
	v_cvt_pk_bf16_f32 v45, v130, v131
	v_cvt_pk_bf16_f32 v44, v127, v132
	v_max_f32_e64 v130, |v130|, |v131|
	v_max_f32_e64 v127, |v127|, |v132|
	v_cvt_pk_bf16_f32 v43, v133, v129
	v_cvt_pk_bf16_f32 v42, v128, v134
	v_max3_f32 v126, v126, v130, v127
	v_max_f32_e64 v127, |v133|, |v129|
	v_max_f32_e64 v128, |v128|, |v134|
	v_max3_f32 v126, v126, v127, v128
	s_waitcnt vmcnt(9)
	v_lshlrev_b32_e32 v127, 16, v38
	v_and_b32_e32 v38, 0xffff0000, v38
	v_lshlrev_b32_e32 v128, 16, v39
	v_and_b32_e32 v39, 0xffff0000, v39
	v_lshlrev_b32_e32 v129, 16, v40
	v_and_b32_e32 v40, 0xffff0000, v40
	v_lshlrev_b32_e32 v130, 16, v41
	v_and_b32_e32 v41, 0xffff0000, v41
	v_add_f32_e32 v131, v127, v38
	v_sub_f32_e32 v38, v127, v38
	v_add_f32_e32 v127, v128, v39
	v_sub_f32_e32 v39, v128, v39
	v_add_f32_e32 v128, v129, v40
	v_sub_f32_e32 v40, v129, v40
	v_add_f32_e32 v129, v130, v41
	v_sub_f32_e32 v41, v130, v41
	v_add_f32_e32 v130, v131, v127
	v_sub_f32_e32 v127, v131, v127
	v_add_f32_e32 v131, v38, v39
	v_sub_f32_e32 v38, v38, v39
	v_add_f32_e32 v39, v128, v129
	v_sub_f32_e32 v128, v128, v129
	v_add_f32_e32 v129, v40, v41
	v_sub_f32_e32 v40, v40, v41
	v_mul_f32_e32 v130, 0.5, v130
	v_mul_f32_e32 v131, 0.5, v131
	v_mul_f32_e32 v127, 0.5, v127
	v_mul_f32_e32 v132, 0.5, v38
	v_mul_f32_e32 v133, 0.5, v39
	v_mul_f32_e32 v129, 0.5, v129
	v_mul_f32_e32 v128, 0.5, v128
	v_mul_f32_e32 v134, 0.5, v40
	v_cvt_pk_bf16_f32 v41, v130, v131
	v_cvt_pk_bf16_f32 v40, v127, v132
	v_max_f32_e64 v130, |v130|, |v131|
	v_max_f32_e64 v127, |v127|, |v132|
	v_cvt_pk_bf16_f32 v39, v133, v129
	v_cvt_pk_bf16_f32 v38, v128, v134
	v_max3_f32 v126, v126, v130, v127
	v_max_f32_e64 v127, |v133|, |v129|
	v_max_f32_e64 v128, |v128|, |v134|
	v_max3_f32 v126, v126, v127, v128
	s_waitcnt vmcnt(8)
	v_lshlrev_b32_e32 v127, 16, v34
	v_and_b32_e32 v34, 0xffff0000, v34
	v_lshlrev_b32_e32 v128, 16, v35
	v_and_b32_e32 v35, 0xffff0000, v35
	v_lshlrev_b32_e32 v129, 16, v36
	v_and_b32_e32 v36, 0xffff0000, v36
	v_lshlrev_b32_e32 v130, 16, v37
	v_and_b32_e32 v37, 0xffff0000, v37
	v_add_f32_e32 v131, v127, v34
	v_sub_f32_e32 v34, v127, v34
	v_add_f32_e32 v127, v128, v35
	v_sub_f32_e32 v35, v128, v35
	v_add_f32_e32 v128, v129, v36
	v_sub_f32_e32 v36, v129, v36
	v_add_f32_e32 v129, v130, v37
	v_sub_f32_e32 v37, v130, v37
	v_add_f32_e32 v130, v131, v127
	v_sub_f32_e32 v127, v131, v127
	v_add_f32_e32 v131, v34, v35
	v_sub_f32_e32 v34, v34, v35
	v_add_f32_e32 v35, v128, v129
	v_sub_f32_e32 v128, v128, v129
	v_add_f32_e32 v129, v36, v37
	v_sub_f32_e32 v36, v36, v37
	v_mul_f32_e32 v130, 0.5, v130
	v_mul_f32_e32 v131, 0.5, v131
	v_mul_f32_e32 v127, 0.5, v127
	v_mul_f32_e32 v132, 0.5, v34
	v_mul_f32_e32 v133, 0.5, v35
	v_mul_f32_e32 v129, 0.5, v129
	v_mul_f32_e32 v128, 0.5, v128
	v_mul_f32_e32 v134, 0.5, v36
	v_cvt_pk_bf16_f32 v37, v130, v131
	v_cvt_pk_bf16_f32 v36, v127, v132
	v_max_f32_e64 v130, |v130|, |v131|
	v_max_f32_e64 v127, |v127|, |v132|
	v_cvt_pk_bf16_f32 v35, v133, v129
	v_cvt_pk_bf16_f32 v34, v128, v134
	v_max3_f32 v126, v126, v130, v127
	v_max_f32_e64 v127, |v133|, |v129|
	v_max_f32_e64 v128, |v128|, |v134|
	v_max3_f32 v126, v126, v127, v128
	s_waitcnt vmcnt(7)
; __device__ __forceinline__ unsigned cvt_pk_bf16(float lo, float hi) { unsigned r; asm volatile("v_cvt_pk_bf16_f32 %0, %1, %2" : "=v"(r) : "v"(lo), "v"(hi)); return r; }
; #define FW_Q(f) { if (ROT >= 4) f = bflyq1(f, u1); if (ROT >= 5) f = bflyq2(f, u2); f *= sc; }
; #define FW_Q(f) { if (ROT >= 4) f = bflyq1(f, u1); if (ROT >= 5) f = bflyq2(f, u2); f *= sc; }
; template <int ROT>
; __device__ __forceinline__ void quant_hid_rot(Frame& F, const bf16_t* hidp, unsigned char* hq, float* sh) {
;     ...
; #pragma unroll
;         for (int j = 0; j < 22; ++j) {
;             float f0 = __uint_as_float(v[j].x << 16), f1 = __uint_as_float(v[j].x & 0xffff0000u), f2 = __uint_as_float(v[j].y << 16), f3 = __uint_as_float(v[j].y & 0xffff0000u);
;             float f4 = __uint_as_float(v[j].z << 16), f5 = __uint_as_float(v[j].z & 0xffff0000u), f6 = __uint_as_float(v[j].w << 16), f7 = __uint_as_float(v[j].w & 0xffff0000u);
;             if (ROT) {
;     ...
;                 FW_BF(f0, f1) FW_BF(f2, f3) FW_BF(f4, f5) FW_BF(f6, f7)
;                 if (ROT >= 2) { FW_BF(f0, f2) FW_BF(f1, f3) FW_BF(f4, f6) FW_BF(f5, f7) }
;                 if (ROT >= 3) { FW_BF(f0, f4) FW_BF(f1, f5) FW_BF(f2, f6) FW_BF(f3, f7) }
;     ...
;                 const float sc = (ROT == 1 ? 0.70710678118654752f : ROT == 2 ? 0.5f : ROT == 3 ? 0.35355339059327373f : ROT == 4 ? 0.25f : 0.17677669529663687f);
;     ...
;                 FW_Q(f0) FW_Q(f1) FW_Q(f2) FW_Q(f3) FW_Q(f4) FW_Q(f5) FW_Q(f6) FW_Q(f7)
;     ...
;                 u32x4 w; w.x = cvt_pk_bf16(f0, f1); w.y = cvt_pk_bf16(f2, f3); w.z = cvt_pk_bf16(f4, f5); w.w = cvt_pk_bf16(f6, f7);
;                 v[j] = w;
;             }
;             am = fmaxf(fmaxf(am, fmaxf(__builtin_fabsf(f0), __builtin_fabsf(f1))), fmaxf(__builtin_fabsf(f2), __builtin_fabsf(f3)));
;             am = fmaxf(fmaxf(am, fmaxf(__builtin_fabsf(f4), __builtin_fabsf(f5))), fmaxf(__builtin_fabsf(f6), __builtin_fabsf(f7)));
;         }
	v_lshlrev_b32_e32 v127, 16, v30
	v_and_b32_e32 v30, 0xffff0000, v30
	v_lshlrev_b32_e32 v128, 16, v31
	v_and_b32_e32 v31, 0xffff0000, v31
	v_lshlrev_b32_e32 v129, 16, v32
	v_and_b32_e32 v32, 0xffff0000, v32
	v_lshlrev_b32_e32 v130, 16, v33
	v_and_b32_e32 v33, 0xffff0000, v33
	v_add_f32_e32 v131, v127, v30
	v_sub_f32_e32 v30, v127, v30
	v_add_f32_e32 v127, v128, v31
	v_sub_f32_e32 v31, v128, v31
	v_add_f32_e32 v128, v129, v32
	v_sub_f32_e32 v32, v129, v32
	v_add_f32_e32 v129, v130, v33
	v_sub_f32_e32 v33, v130, v33
	v_add_f32_e32 v130, v131, v127
	v_sub_f32_e32 v127, v131, v127
	v_add_f32_e32 v131, v30, v31
	v_sub_f32_e32 v30, v30, v31
	v_add_f32_e32 v31, v128, v129
	v_sub_f32_e32 v128, v128, v129
	v_add_f32_e32 v129, v32, v33
	v_sub_f32_e32 v32, v32, v33
	v_mul_f32_e32 v130, 0.5, v130
	v_mul_f32_e32 v131, 0.5, v131
	v_mul_f32_e32 v127, 0.5, v127
	v_mul_f32_e32 v132, 0.5, v30
	v_mul_f32_e32 v133, 0.5, v31
	v_mul_f32_e32 v129, 0.5, v129
	v_mul_f32_e32 v128, 0.5, v128
	v_mul_f32_e32 v134, 0.5, v32
	v_cvt_pk_bf16_f32 v33, v130, v131
	v_cvt_pk_bf16_f32 v32, v127, v132
	v_max_f32_e64 v130, |v130|, |v131|
	v_max_f32_e64 v127, |v127|, |v132|
	v_cvt_pk_bf16_f32 v31, v133, v129
	v_cvt_pk_bf16_f32 v30, v128, v134
	v_max3_f32 v126, v126, v130, v127
	v_max_f32_e64 v127, |v133|, |v129|
	v_max_f32_e64 v128, |v128|, |v134|
	v_max3_f32 v126, v126, v127, v128
	s_waitcnt vmcnt(6)
	v_lshlrev_b32_e32 v127, 16, v26
	v_and_b32_e32 v26, 0xffff0000, v26
	v_lshlrev_b32_e32 v128, 16, v27
	v_and_b32_e32 v27, 0xffff0000, v27
	v_lshlrev_b32_e32 v129, 16, v28
	v_and_b32_e32 v28, 0xffff0000, v28
	v_lshlrev_b32_e32 v130, 16, v29
	v_and_b32_e32 v29, 0xffff0000, v29
	v_add_f32_e32 v131, v127, v26
	v_sub_f32_e32 v26, v127, v26
	v_add_f32_e32 v127, v128, v27
	v_sub_f32_e32 v27, v128, v27
	v_add_f32_e32 v128, v129, v28
	v_sub_f32_e32 v28, v129, v28
	v_add_f32_e32 v129, v130, v29
	v_sub_f32_e32 v29, v130, v29
	v_add_f32_e32 v130, v131, v127
	v_sub_f32_e32 v127, v131, v127
	v_add_f32_e32 v131, v26, v27
	v_sub_f32_e32 v26, v26, v27
	v_add_f32_e32 v27, v128, v129
	v_sub_f32_e32 v128, v128, v129
	v_add_f32_e32 v129, v28, v29
	v_sub_f32_e32 v28, v28, v29
	v_mul_f32_e32 v130, 0.5, v130
	v_mul_f32_e32 v131, 0.5, v131
	v_mul_f32_e32 v127, 0.5, v127
	v_mul_f32_e32 v132, 0.5, v26
	v_mul_f32_e32 v133, 0.5, v27
	v_mul_f32_e32 v129, 0.5, v129
	v_mul_f32_e32 v128, 0.5, v128
	v_mul_f32_e32 v134, 0.5, v28
	v_cvt_pk_bf16_f32 v29, v130, v131
	v_cvt_pk_bf16_f32 v28, v127, v132
	v_max_f32_e64 v130, |v130|, |v131|
	v_max_f32_e64 v127, |v127|, |v132|
	v_cvt_pk_bf16_f32 v27, v133, v129
	v_cvt_pk_bf16_f32 v26, v128, v134
	v_max3_f32 v126, v126, v130, v127
	v_max_f32_e64 v127, |v133|, |v129|
	v_max_f32_e64 v128, |v128|, |v134|
	v_max3_f32 v126, v126, v127, v128
	s_waitcnt vmcnt(5)
	v_lshlrev_b32_e32 v127, 16, v22
	v_and_b32_e32 v22, 0xffff0000, v22
	v_lshlrev_b32_e32 v128, 16, v23
	v_and_b32_e32 v23, 0xffff0000, v23
	v_lshlrev_b32_e32 v129, 16, v24
	v_and_b32_e32 v24, 0xffff0000, v24
	v_lshlrev_b32_e32 v130, 16, v25
	v_and_b32_e32 v25, 0xffff0000, v25
	v_add_f32_e32 v131, v127, v22
	v_sub_f32_e32 v22, v127, v22
	v_add_f32_e32 v127, v128, v23
	v_sub_f32_e32 v23, v128, v23
	v_add_f32_e32 v128, v129, v24
	v_sub_f32_e32 v24, v129, v24
	v_add_f32_e32 v129, v130, v25
	v_sub_f32_e32 v25, v130, v25
	v_add_f32_e32 v130, v131, v127
	v_sub_f32_e32 v127, v131, v127
	v_add_f32_e32 v131, v22, v23
	v_sub_f32_e32 v22, v22, v23
	v_add_f32_e32 v23, v128, v129
	v_sub_f32_e32 v128, v128, v129
	v_add_f32_e32 v129, v24, v25
	v_sub_f32_e32 v24, v24, v25
	v_mul_f32_e32 v25, 0.5, v130
	v_mul_f32_e32 v130, 0.5, v131
	v_mul_f32_e32 v127, 0.5, v127
	v_mul_f32_e32 v22, 0.5, v22
	v_mul_f32_e32 v23, 0.5, v23
	v_mul_f32_e32 v129, 0.5, v129
	v_mul_f32_e32 v131, 0.5, v128
	v_mul_f32_e32 v24, 0.5, v24
	v_max_f32_e64 v128, |v25|, |v130|
	v_max_f32_e64 v132, |v127|, |v22|
	v_max3_f32 v126, v126, v128, v132
	v_max_f32_e64 v128, |v23|, |v129|
	v_max_f32_e64 v132, |v131|, |v24|
	v_max3_f32 v126, v126, v128, v132
	s_waitcnt vmcnt(4)
	v_lshlrev_b32_e32 v128, 16, v18
	v_and_b32_e32 v18, 0xffff0000, v18
	v_lshlrev_b32_e32 v132, 16, v19
	v_and_b32_e32 v19, 0xffff0000, v19
	v_lshlrev_b32_e32 v133, 16, v20
	v_and_b32_e32 v20, 0xffff0000, v20
	v_lshlrev_b32_e32 v134, 16, v21
	v_and_b32_e32 v21, 0xffff0000, v21
	v_add_f32_e32 v135, v128, v18
	v_sub_f32_e32 v18, v128, v18
	v_add_f32_e32 v128, v132, v19
	v_sub_f32_e32 v19, v132, v19
	v_add_f32_e32 v132, v133, v20
	v_sub_f32_e32 v20, v133, v20
	v_add_f32_e32 v133, v134, v21
	v_sub_f32_e32 v21, v134, v21
	v_add_f32_e32 v134, v135, v128
	v_sub_f32_e32 v128, v135, v128
	v_add_f32_e32 v135, v18, v19
	v_sub_f32_e32 v18, v18, v19
	v_add_f32_e32 v19, v132, v133
	v_sub_f32_e32 v132, v132, v133
	v_add_f32_e32 v133, v20, v21
	v_sub_f32_e32 v20, v20, v21
	v_mul_f32_e32 v21, 0.5, v134
	v_mul_f32_e32 v134, 0.5, v135
	v_mul_f32_e32 v135, 0.5, v128
	v_mul_f32_e32 v18, 0.5, v18
	v_mul_f32_e32 v19, 0.5, v19
	v_mul_f32_e32 v133, 0.5, v133
	v_mul_f32_e32 v132, 0.5, v132
	v_mul_f32_e32 v20, 0.5, v20
	v_max_f32_e64 v128, |v21|, |v134|
	v_max_f32_e64 v136, |v135|, |v18|
	v_max3_f32 v126, v126, v128, v136
	v_max_f32_e64 v128, |v19|, |v133|
	v_max_f32_e64 v136, |v132|, |v20|
	v_max3_f32 v126, v126, v128, v136
	s_waitcnt vmcnt(3)
; template <int ROT>
; __device__ __forceinline__ void quant_hid_rot(Frame& F, const bf16_t* hidp, unsigned char* hq, float* sh) {
;     ...
;             am = fmaxf(fmaxf(am, fmaxf(__builtin_fabsf(f0), __builtin_fabsf(f1))), fmaxf(__builtin_fabsf(f2), __builtin_fabsf(f3)));
;             am = fmaxf(fmaxf(am, fmaxf(__builtin_fabsf(f4), __builtin_fabsf(f5))), fmaxf(__builtin_fabsf(f6), __builtin_fabsf(f7)));
;         }
; #pragma unroll
;         for (int o = 1; o < 64; o <<= 1) am = fmaxf(am, __shfl_xor(am, o));
;         am *= 1.00390625f;
;         const float inv = am > 0.f ? 127.0f / am : 0.f;
;         if (lane == 0) sh[row] = am * (1.0f / 127.0f);
	v_lshlrev_b32_e32 v128, 16, v14
	v_and_b32_e32 v14, 0xffff0000, v14
	v_lshlrev_b32_e32 v136, 16, v15
	v_and_b32_e32 v15, 0xffff0000, v15
	v_lshlrev_b32_e32 v137, 16, v16
	v_and_b32_e32 v16, 0xffff0000, v16
	v_lshlrev_b32_e32 v138, 16, v17
	v_and_b32_e32 v17, 0xffff0000, v17
	v_add_f32_e32 v139, v128, v14
	v_sub_f32_e32 v14, v128, v14
	v_add_f32_e32 v128, v136, v15
	v_sub_f32_e32 v15, v136, v15
	v_add_f32_e32 v136, v137, v16
	v_sub_f32_e32 v16, v137, v16
	v_add_f32_e32 v137, v138, v17
	v_sub_f32_e32 v17, v138, v17
	v_add_f32_e32 v138, v139, v128
	v_sub_f32_e32 v128, v139, v128
	v_add_f32_e32 v139, v14, v15
	v_sub_f32_e32 v14, v14, v15
	v_add_f32_e32 v15, v136, v137
	v_sub_f32_e32 v136, v136, v137
	v_add_f32_e32 v137, v16, v17
	v_sub_f32_e32 v16, v16, v17
	v_mul_f32_e32 v17, 0.5, v138
	v_mul_f32_e32 v138, 0.5, v139
	v_mul_f32_e32 v139, 0.5, v128
	v_mul_f32_e32 v14, 0.5, v14
	v_mul_f32_e32 v15, 0.5, v15
	v_mul_f32_e32 v137, 0.5, v137
	v_mul_f32_e32 v136, 0.5, v136
	v_mul_f32_e32 v16, 0.5, v16
	v_max_f32_e64 v128, |v17|, |v138|
	v_max_f32_e64 v140, |v139|, |v14|
	v_max3_f32 v126, v126, v128, v140
	v_max_f32_e64 v128, |v15|, |v137|
	v_max_f32_e64 v140, |v136|, |v16|
	v_max3_f32 v126, v126, v128, v140
	s_waitcnt vmcnt(2)
	v_lshlrev_b32_e32 v128, 16, v10
	v_and_b32_e32 v10, 0xffff0000, v10
	v_lshlrev_b32_e32 v140, 16, v11
	v_and_b32_e32 v11, 0xffff0000, v11
	v_lshlrev_b32_e32 v141, 16, v12
	v_and_b32_e32 v12, 0xffff0000, v12
	v_lshlrev_b32_e32 v142, 16, v13
	v_and_b32_e32 v13, 0xffff0000, v13
	v_add_f32_e32 v143, v128, v10
	v_sub_f32_e32 v10, v128, v10
	v_add_f32_e32 v128, v140, v11
	v_sub_f32_e32 v11, v140, v11
	v_add_f32_e32 v140, v141, v12
	v_sub_f32_e32 v12, v141, v12
	v_add_f32_e32 v141, v142, v13
	v_sub_f32_e32 v13, v142, v13
	v_add_f32_e32 v142, v143, v128
	v_sub_f32_e32 v128, v143, v128
	v_add_f32_e32 v143, v10, v11
	v_sub_f32_e32 v10, v10, v11
	v_add_f32_e32 v11, v140, v141
	v_sub_f32_e32 v140, v140, v141
	v_add_f32_e32 v141, v12, v13
	v_sub_f32_e32 v12, v12, v13
	v_mul_f32_e32 v13, 0.5, v142
	v_mul_f32_e32 v142, 0.5, v143
	v_mul_f32_e32 v143, 0.5, v128
	v_mul_f32_e32 v10, 0.5, v10
	v_mul_f32_e32 v11, 0.5, v11
	v_mul_f32_e32 v141, 0.5, v141
	v_mul_f32_e32 v140, 0.5, v140
	v_mul_f32_e32 v12, 0.5, v12
	v_max_f32_e64 v128, |v13|, |v142|
	v_max_f32_e64 v144, |v143|, |v10|
	v_max3_f32 v126, v126, v128, v144
	v_max_f32_e64 v128, |v11|, |v141|
	v_max_f32_e64 v144, |v140|, |v12|
	v_max3_f32 v126, v126, v128, v144
	s_waitcnt vmcnt(1)
	v_lshlrev_b32_e32 v128, 16, v6
	v_and_b32_e32 v6, 0xffff0000, v6
	v_lshlrev_b32_e32 v144, 16, v7
	v_and_b32_e32 v7, 0xffff0000, v7
	v_lshlrev_b32_e32 v145, 16, v8
	v_and_b32_e32 v8, 0xffff0000, v8
	v_lshlrev_b32_e32 v146, 16, v9
	v_and_b32_e32 v9, 0xffff0000, v9
	v_add_f32_e32 v147, v128, v6
	v_sub_f32_e32 v6, v128, v6
	v_add_f32_e32 v128, v144, v7
	v_sub_f32_e32 v7, v144, v7
	v_add_f32_e32 v144, v145, v8
	v_sub_f32_e32 v8, v145, v8
	v_add_f32_e32 v145, v146, v9
	v_sub_f32_e32 v9, v146, v9
	v_add_f32_e32 v146, v147, v128
	v_sub_f32_e32 v128, v147, v128
	v_add_f32_e32 v147, v6, v7
	v_sub_f32_e32 v6, v6, v7
	v_add_f32_e32 v7, v144, v145
	v_sub_f32_e32 v144, v144, v145
	v_add_f32_e32 v145, v8, v9
	v_sub_f32_e32 v8, v8, v9
	v_mul_f32_e32 v9, 0.5, v146
	v_mul_f32_e32 v146, 0.5, v147
	v_mul_f32_e32 v147, 0.5, v128
	v_mul_f32_e32 v148, 0.5, v6
	v_mul_f32_e32 v149, 0.5, v7
	v_mul_f32_e32 v145, 0.5, v145
	v_mul_f32_e32 v144, 0.5, v144
	v_mul_f32_e32 v8, 0.5, v8
	v_max_f32_e64 v6, |v9|, |v146|
	v_max_f32_e64 v7, |v147|, |v148|
	v_max3_f32 v6, v126, v6, v7
	v_max_f32_e64 v7, |v149|, |v145|
	v_max_f32_e64 v126, |v144|, |v8|
	v_max3_f32 v126, v6, v7, v126
	s_waitcnt vmcnt(0)
	v_lshlrev_b32_e32 v6, 16, v2
	v_and_b32_e32 v2, 0xffff0000, v2
	v_lshlrev_b32_e32 v7, 16, v3
	v_and_b32_e32 v3, 0xffff0000, v3
	v_add_f32_e32 v128, v6, v2
	v_sub_f32_e32 v150, v6, v2
	v_add_f32_e32 v151, v7, v3
	v_sub_f32_e32 v152, v7, v3
	v_lshlrev_b32_e32 v3, 16, v5
	v_lshlrev_b32_e32 v2, 16, v4
	v_and_b32_e32 v5, 0xffff0000, v5
	v_and_b32_e32 v4, 0xffff0000, v4
	v_pk_add_f32 v[6:7], v[2:3], v[4:5]
	v_pk_add_f32 v[2:3], v[2:3], v[4:5] neg_lo:[0,1] neg_hi:[0,1]
	v_add_f32_e32 v4, v128, v151
	v_sub_f32_e32 v5, v128, v151
	v_add_f32_e32 v128, v150, v152
	v_sub_f32_e32 v150, v150, v152
	v_add_f32_e32 v151, v6, v7
	v_sub_f32_e32 v6, v6, v7
	v_add_f32_e32 v7, v2, v3
	v_sub_f32_e32 v2, v2, v3
	v_mul_f32_e32 v3, 0.5, v4
	v_mul_f32_e32 v4, 0.5, v128
	v_mul_f32_e32 v5, 0.5, v5
	v_mul_f32_e32 v150, 0.5, v150
	v_mul_f32_e32 v151, 0.5, v151
	v_mul_f32_e32 v152, 0.5, v7
	v_mul_f32_e32 v153, 0.5, v6
	v_mul_f32_e32 v2, 0.5, v2
	v_max_f32_e64 v6, |v3|, |v4|
	v_max_f32_e64 v7, |v5|, |v150|
	v_max3_f32 v6, v126, v6, v7
	v_max_f32_e64 v7, |v151|, |v152|
	v_max_f32_e64 v126, |v153|, |v2|
	v_cmp_lt_i32_e32 vcc, v104, v103
	v_max3_f32 v6, v6, v7, v126
	v_cvt_pk_bf16_f32 v128, v25, v130
	v_cvt_pk_bf16_f32 v127, v127, v22
	v_cvt_pk_bf16_f32 v126, v23, v129
	v_cvt_pk_bf16_f32 v25, v131, v24
	s_nop 0
	v_cndmask_b32_e32 v7, v102, v104, vcc
	v_lshlrev_b32_e32 v7, 2, v7
	ds_bpermute_b32 v7, v7, v6
	v_cmp_lt_i32_e32 vcc, v105, v103
	v_cvt_pk_bf16_f32 v24, v21, v134
	v_cvt_pk_bf16_f32 v23, v135, v18
	v_cvt_pk_bf16_f32 v22, v19, v133
	s_waitcnt lgkmcnt(0)
	v_max_f32_e32 v7, v7, v7
	v_max_f32_e32 v6, v6, v7
	v_cndmask_b32_e32 v7, v102, v105, vcc
	v_lshlrev_b32_e32 v7, 2, v7
	ds_bpermute_b32 v7, v7, v6
	v_cmp_lt_i32_e32 vcc, v106, v103
	v_cvt_pk_bf16_f32 v21, v132, v20
	v_cvt_pk_bf16_f32 v20, v17, v138
	v_cvt_pk_bf16_f32 v19, v139, v14
	s_waitcnt lgkmcnt(0)
	v_max_f32_e32 v7, v7, v7
	v_max_f32_e32 v6, v6, v7
	v_cndmask_b32_e32 v7, v102, v106, vcc
	v_lshlrev_b32_e32 v7, 2, v7
	ds_bpermute_b32 v7, v7, v6
	v_cmp_lt_i32_e32 vcc, v107, v103
	v_cvt_pk_bf16_f32 v18, v15, v137
	v_cvt_pk_bf16_f32 v17, v136, v16
	v_cvt_pk_bf16_f32 v16, v13, v142
	s_waitcnt lgkmcnt(0)
	v_max_f32_e32 v7, v7, v7
	v_max_f32_e32 v6, v6, v7
	v_cndmask_b32_e32 v7, v102, v107, vcc
	v_lshlrev_b32_e32 v7, 2, v7
	ds_bpermute_b32 v7, v7, v6
	v_cmp_lt_i32_e32 vcc, v108, v103
	v_cvt_pk_bf16_f32 v15, v143, v10
	v_cvt_pk_bf16_f32 v14, v11, v141
	v_cvt_pk_bf16_f32 v13, v140, v12
	s_waitcnt lgkmcnt(0)
	v_max_f32_e32 v7, v7, v7
	v_max_f32_e32 v6, v6, v7
	v_cndmask_b32_e32 v7, v102, v108, vcc
	v_lshlrev_b32_e32 v7, 2, v7
	ds_bpermute_b32 v7, v7, v6
	v_cmp_lt_i32_e32 vcc, v109, v103
	v_cvt_pk_bf16_f32 v12, v9, v146
	v_cvt_pk_bf16_f32 v11, v147, v148
	v_cvt_pk_bf16_f32 v10, v149, v145
	s_waitcnt lgkmcnt(0)
	v_max_f32_e32 v7, v7, v7
	v_cvt_pk_bf16_f32 v9, v144, v8
	v_max_f32_e32 v8, v6, v7
	v_cndmask_b32_e32 v6, v102, v109, vcc
	v_lshlrev_b32_e32 v6, 2, v6
	ds_bpermute_b32 v129, v6, v8
	v_cvt_pk_bf16_f32 v7, v3, v4
	v_cvt_pk_bf16_f32 v6, v5, v150
	v_cvt_pk_bf16_f32 v5, v151, v152
	v_cvt_pk_bf16_f32 v4, v153, v2
	s_waitcnt lgkmcnt(0)
	v_max_f32_e32 v2, v129, v129
	v_max_f32_e32 v2, v8, v2
	v_mul_f32_e32 v2, 0x3f808000, v2
	s_and_saveexec_b64 s[14:15], s[2:3]
	s_cbranch_execz .LBB0_1313
	v_mul_f32_e32 v3, 0x3c010204, v2
	global_store_dword v75, v3, s[10:11]

; __host__ __device__ __forceinline__ size_t blk_off(int r, int k, int KT) { return ((size_t)((r >> 8) * KT + (k >> 6)) * 256 + (size_t)(r & 255)) * 64 + (size_t)(k & 63); }
; __device__ __forceinline__ float rs_from_acc(u64 a) { return __builtin_amdgcn_rsqf((float)a * (1.0f / (4294967296.0f * 4096.0f)) + EPS); }
; __global__ void __launch_bounds__(512, 2) mk_fwd(Args args) {
;     ...
;         for (int m = gw; m < M; m += NGW) {
;             const float r = rs_from_acc(racc3[m]);
;             const bf16_t* src = actb + blk_off(m, 64 * kq, KT4) + 8 * c;
;             u32x4 v[8];
; #pragma unroll
;             for (int j = 0; j < 8; ++j) v[j] = *(const u32x4*)(src + (size_t)(8 * j) * (256 * 64));
; #pragma unroll
;             for (int j = 0; j < 8; ++j) {
;                 const int k = 64 * (8 * j + kq) + 8 * c;
;                 const f32x4 g0 = *(const f32x4*)(gn + k), g1 = *(const f32x4*)(gn + k + 4);
;                 f32x4 o0, o1;
;                 o0[0] = __uint_as_float(v[j].x << 16); o0[1] = __uint_as_float(v[j].x & 0xffff0000u); o0[2] = __uint_as_float(v[j].y << 16); o0[3] = __uint_as_float(v[j].y & 0xffff0000u);
;                 o1[0] = __uint_as_float(v[j].z << 16); o1[1] = __uint_as_float(v[j].z & 0xffff0000u); o1[2] = __uint_as_float(v[j].w << 16); o1[3] = __uint_as_float(v[j].w & 0xffff0000u);
;                 float* dst = F.out + (size_t)m * DM + k;
;                 *(f32x4*)dst = o0 * r * g0; *(f32x4*)(dst + 4) = o1 * r * g1;
;             }
.LBB0_4248:
	global_load_dwordx2 v[74:75], v13, s[6:7]
	s_ashr_i32 s4, s0, 2
	s_and_b32 s22, s4, 0xffffffc0
	v_or_b32_e32 v0, s22, v43
	v_ashrrev_i32_e32 v1, 31, v0
	s_and_b32 s21, s14, 0x3fc0
	v_lshlrev_b64 v[0:1], 15, v[0:1]
	s_lshl_b32 s4, s21, 1
	v_lshl_add_u64 v[0:1], s[72:73], 0, v[0:1]
	v_lshl_add_u64 v[0:1], v[0:1], 0, s[4:5]
	v_lshl_add_u64 v[0:1], v[0:1], 0, v[40:41]
	global_load_dwordx4 v[46:49], v[14:15], off offset:16 nt
	global_load_dwordx4 v[50:53], v[14:15], off nt
	global_load_dwordx4 v[54:57], v[0:1], off nt
	v_add_co_u32_e32 v78, vcc, s1, v0
	v_lshl_add_u64 v[76:77], s[10:11], 0, v[12:13]
	s_nop 0
	v_addc_co_u32_e32 v79, vcc, 0, v1, vcc
	v_add_co_u32_e32 v80, vcc, s3, v0
	s_add_i32 s0, s0, s2
	s_nop 0
	v_addc_co_u32_e32 v81, vcc, 0, v1, vcc
	v_add_co_u32_e32 v82, vcc, s16, v0
	s_add_u32 s6, s6, s8
	s_nop 0
	v_addc_co_u32_e32 v83, vcc, 0, v1, vcc
	v_add_co_u32_e32 v84, vcc, s17, v0
	s_addc_u32 s7, s7, s9
	s_nop 0
	v_addc_co_u32_e32 v85, vcc, 0, v1, vcc
	v_add_co_u32_e32 v86, vcc, s18, v0
	s_add_i32 s14, s14, s15
	s_nop 0
	v_addc_co_u32_e32 v87, vcc, 0, v1, vcc
	v_add_co_u32_e32 v88, vcc, s19, v0
	s_waitcnt vmcnt(3)
	v_ffbh_u32_e32 v42, v75
	v_min_u32_e32 v42, 32, v42
	v_lshlrev_b64 v[74:75], v42, v[74:75]
	v_min_u32_e32 v45, 1, v74
	v_or_b32_e32 v45, v75, v45
	v_cvt_f32_u32_e32 v45, v45
	v_sub_u32_e32 v42, 32, v42
	v_addc_co_u32_e32 v89, vcc, 0, v1, vcc
	v_ldexp_f32 v42, v45, v42
	v_fmamk_f32 v42, v42, 0x29800000, v44
	v_rsq_f32_e32 v42, v42
	v_add_co_u32_e32 v90, vcc, s20, v0
	s_waitcnt vmcnt(0)
	v_lshlrev_b32_e32 v74, 16, v54
	v_and_b32_e32 v75, 0xffff0000, v54
	v_lshlrev_b32_e32 v54, 16, v55
	v_and_b32_e32 v55, 0xffff0000, v55
	v_addc_co_u32_e32 v91, vcc, 0, v1, vcc
	global_load_dwordx4 v[58:61], v[78:79], off nt
	global_load_dwordx4 v[62:65], v[80:81], off nt
	global_load_dwordx4 v[66:69], v[82:83], off nt
	global_load_dwordx4 v[70:73], v[84:85], off nt
	global_load_dwordx4 v[8:11], v[86:87], off nt
	global_load_dwordx4 v[4:7], v[88:89], off nt
	global_load_dwordx4 v[0:3], v[90:91], off nt
	v_lshlrev_b32_e32 v78, 16, v56
	v_and_b32_e32 v79, 0xffff0000, v56
	v_lshlrev_b32_e32 v56, 16, v57
	v_and_b32_e32 v57, 0xffff0000, v57
	v_pk_mul_f32 v[74:75], v[42:43], v[74:75] op_sel_hi:[0,1]
	v_pk_mul_f32 v[54:55], v[42:43], v[54:55] op_sel_hi:[0,1]
	v_pk_mul_f32 v[78:79], v[42:43], v[78:79] op_sel_hi:[0,1]
	v_pk_mul_f32 v[56:57], v[42:43], v[56:57] op_sel_hi:[0,1]
	v_pk_mul_f32 v[52:53], v[54:55], v[52:53]
	v_pk_mul_f32 v[50:51], v[74:75], v[50:51]
	v_pk_mul_f32 v[48:49], v[56:57], v[48:49]
	v_pk_mul_f32 v[46:47], v[78:79], v[46:47]
	global_store_dwordx4 v[76:77], v[50:53], off
	global_store_dwordx4 v[76:77], v[46:49], off offset:16
	global_load_dwordx4 v[46:49], v[14:15], off offset:2048 nt
	s_nop 0
	global_load_dwordx4 v[50:53], v[14:15], off offset:2064 nt
	s_waitcnt vmcnt(10)
	v_lshlrev_b32_e32 v54, 16, v58
	v_and_b32_e32 v55, 0xffff0000, v58
	v_lshlrev_b32_e32 v56, 16, v59
	v_and_b32_e32 v57, 0xffff0000, v59
	v_lshlrev_b32_e32 v58, 16, v60
	v_and_b32_e32 v59, 0xffff0000, v60
	v_lshlrev_b32_e32 v60, 16, v61
	v_and_b32_e32 v61, 0xffff0000, v61
	v_pk_mul_f32 v[56:57], v[42:43], v[56:57] op_sel_hi:[0,1]
	v_pk_mul_f32 v[54:55], v[42:43], v[54:55] op_sel_hi:[0,1]
	v_pk_mul_f32 v[60:61], v[42:43], v[60:61] op_sel_hi:[0,1]
	v_pk_mul_f32 v[58:59], v[42:43], v[58:59] op_sel_hi:[0,1]
	s_waitcnt vmcnt(1)
	v_pk_mul_f32 v[46:47], v[54:55], v[46:47]
	v_pk_mul_f32 v[48:49], v[56:57], v[48:49]
	s_waitcnt vmcnt(0)
	v_pk_mul_f32 v[50:51], v[58:59], v[50:51]
	v_pk_mul_f32 v[52:53], v[60:61], v[52:53]
	global_store_dwordx4 v[76:77], v[46:49], off offset:2048
	global_store_dwordx4 v[76:77], v[50:53], off offset:2064
	global_load_dwordx4 v[46:49], v[16:17], off nt
	s_nop 0
	global_load_dwordx4 v[50:53], v[16:17], off offset:16 nt
	v_lshlrev_b32_e32 v56, 16, v62
	v_and_b32_e32 v57, 0xffff0000, v62
	v_lshlrev_b32_e32 v58, 16, v63
	v_and_b32_e32 v59, 0xffff0000, v63
	v_lshlrev_b32_e32 v60, 16, v64
	v_and_b32_e32 v61, 0xffff0000, v64
	v_lshlrev_b32_e32 v62, 16, v65
	v_and_b32_e32 v63, 0xffff0000, v65
	v_pk_mul_f32 v[58:59], v[42:43], v[58:59] op_sel_hi:[0,1]
	v_pk_mul_f32 v[56:57], v[42:43], v[56:57] op_sel_hi:[0,1]
	v_lshl_add_u64 v[54:55], s[10:11], 0, v[36:37]
	v_pk_mul_f32 v[62:63], v[42:43], v[62:63] op_sel_hi:[0,1]
	v_pk_mul_f32 v[60:61], v[42:43], v[60:61] op_sel_hi:[0,1]
	s_waitcnt vmcnt(1)
	v_pk_mul_f32 v[46:47], v[56:57], v[46:47]
	v_pk_mul_f32 v[48:49], v[58:59], v[48:49]
	s_waitcnt vmcnt(0)
; __global__ void __launch_bounds__(512, 2) mk_fwd(Args args) {
;     ...
;             for (int j = 0; j < 8; ++j) {
;                 const int k = 64 * (8 * j + kq) + 8 * c;
;                 const f32x4 g0 = *(const f32x4*)(gn + k), g1 = *(const f32x4*)(gn + k + 4);
;                 f32x4 o0, o1;
;                 o0[0] = __uint_as_float(v[j].x << 16); o0[1] = __uint_as_float(v[j].x & 0xffff0000u); o0[2] = __uint_as_float(v[j].y << 16); o0[3] = __uint_as_float(v[j].y & 0xffff0000u);
;                 o1[0] = __uint_as_float(v[j].z << 16); o1[1] = __uint_as_float(v[j].z & 0xffff0000u); o1[2] = __uint_as_float(v[j].w << 16); o1[3] = __uint_as_float(v[j].w & 0xffff0000u);
;                 float* dst = F.out + (size_t)m * DM + k;
;                 *(f32x4*)dst = o0 * r * g0; *(f32x4*)(dst + 4) = o1 * r * g1;
;             }
	v_pk_mul_f32 v[50:51], v[60:61], v[50:51]
	v_pk_mul_f32 v[52:53], v[62:63], v[52:53]
	global_store_dwordx4 v[54:55], v[46:49], off offset:-16
	global_store_dwordx4 v[54:55], v[50:53], off
	global_load_dwordx4 v[46:49], v[18:19], off nt
	s_nop 0
	global_load_dwordx4 v[50:53], v[18:19], off offset:16 nt
	v_lshlrev_b32_e32 v56, 16, v66
	v_and_b32_e32 v57, 0xffff0000, v66
	v_lshlrev_b32_e32 v58, 16, v67
	v_and_b32_e32 v59, 0xffff0000, v67
	v_lshlrev_b32_e32 v60, 16, v68
	v_and_b32_e32 v61, 0xffff0000, v68
	v_lshlrev_b32_e32 v62, 16, v69
	v_and_b32_e32 v63, 0xffff0000, v69
	v_pk_mul_f32 v[58:59], v[42:43], v[58:59] op_sel_hi:[0,1]
	v_pk_mul_f32 v[56:57], v[42:43], v[56:57] op_sel_hi:[0,1]
	v_lshl_add_u64 v[54:55], s[10:11], 0, v[38:39]
	v_pk_mul_f32 v[62:63], v[42:43], v[62:63] op_sel_hi:[0,1]
	v_pk_mul_f32 v[60:61], v[42:43], v[60:61] op_sel_hi:[0,1]
	s_waitcnt vmcnt(1)
	v_pk_mul_f32 v[46:47], v[56:57], v[46:47]
	v_pk_mul_f32 v[48:49], v[58:59], v[48:49]
	s_waitcnt vmcnt(0)
	v_pk_mul_f32 v[50:51], v[60:61], v[50:51]
	v_pk_mul_f32 v[52:53], v[62:63], v[52:53]
	global_store_dwordx4 v[54:55], v[46:49], off offset:-16
	global_store_dwordx4 v[54:55], v[50:53], off
	global_load_dwordx4 v[46:49], v[22:23], off nt
	s_nop 0
	global_load_dwordx4 v[50:53], v[22:23], off offset:16 nt
	v_lshlrev_b32_e32 v56, 16, v70
	v_and_b32_e32 v57, 0xffff0000, v70
	v_lshlrev_b32_e32 v58, 16, v71
	v_and_b32_e32 v59, 0xffff0000, v71
	v_lshlrev_b32_e32 v60, 16, v72
	v_and_b32_e32 v61, 0xffff0000, v72
	v_lshlrev_b32_e32 v62, 16, v73
	v_and_b32_e32 v63, 0xffff0000, v73
	v_pk_mul_f32 v[58:59], v[42:43], v[58:59] op_sel_hi:[0,1]
	v_pk_mul_f32 v[56:57], v[42:43], v[56:57] op_sel_hi:[0,1]
	v_lshl_add_u64 v[54:55], s[10:11], 0, v[20:21]
	v_pk_mul_f32 v[62:63], v[42:43], v[62:63] op_sel_hi:[0,1]
	v_pk_mul_f32 v[60:61], v[42:43], v[60:61] op_sel_hi:[0,1]
	s_waitcnt vmcnt(1)
	v_pk_mul_f32 v[46:47], v[56:57], v[46:47]
	v_pk_mul_f32 v[48:49], v[58:59], v[48:49]
	s_waitcnt vmcnt(0)
	v_pk_mul_f32 v[50:51], v[60:61], v[50:51]
	v_pk_mul_f32 v[52:53], v[62:63], v[52:53]
	global_store_dwordx4 v[54:55], v[46:49], off
	global_store_dwordx4 v[54:55], v[50:53], off offset:16
	global_load_dwordx4 v[46:49], v[26:27], off nt
	s_nop 0
	global_load_dwordx4 v[50:53], v[26:27], off offset:16 nt
	v_lshlrev_b32_e32 v56, 16, v8
	v_and_b32_e32 v57, 0xffff0000, v8
	v_lshlrev_b32_e32 v8, 16, v9
	v_and_b32_e32 v9, 0xffff0000, v9
	v_lshlrev_b32_e32 v58, 16, v10
	v_and_b32_e32 v59, 0xffff0000, v10
	v_lshlrev_b32_e32 v10, 16, v11
	v_and_b32_e32 v11, 0xffff0000, v11
	v_pk_mul_f32 v[60:61], v[42:43], v[8:9] op_sel_hi:[0,1]
	v_pk_mul_f32 v[8:9], v[42:43], v[56:57] op_sel_hi:[0,1]
	v_lshl_add_u64 v[54:55], s[10:11], 0, v[24:25]
	v_pk_mul_f32 v[56:57], v[42:43], v[10:11] op_sel_hi:[0,1]
	v_pk_mul_f32 v[58:59], v[42:43], v[58:59] op_sel_hi:[0,1]
	s_waitcnt vmcnt(1)
	v_pk_mul_f32 v[8:9], v[8:9], v[46:47]
	v_pk_mul_f32 v[10:11], v[60:61], v[48:49]
	s_waitcnt vmcnt(0)
	v_pk_mul_f32 v[46:47], v[58:59], v[50:51]
	v_pk_mul_f32 v[48:49], v[56:57], v[52:53]
	global_store_dwordx4 v[54:55], v[8:11], off
	global_store_dwordx4 v[54:55], v[46:49], off offset:16
	global_load_dwordx4 v[8:11], v[30:31], off nt
	s_nop 0
	global_load_dwordx4 v[46:49], v[30:31], off offset:16 nt
	v_lshlrev_b32_e32 v52, 16, v4
	v_and_b32_e32 v53, 0xffff0000, v4
	v_lshlrev_b32_e32 v4, 16, v5
	v_and_b32_e32 v5, 0xffff0000, v5
	v_lshlrev_b32_e32 v54, 16, v6
	v_and_b32_e32 v55, 0xffff0000, v6
	v_lshlrev_b32_e32 v6, 16, v7
	v_and_b32_e32 v7, 0xffff0000, v7
	v_pk_mul_f32 v[56:57], v[42:43], v[4:5] op_sel_hi:[0,1]
	v_pk_mul_f32 v[4:5], v[42:43], v[52:53] op_sel_hi:[0,1]
	v_lshl_add_u64 v[50:51], s[10:11], 0, v[28:29]
	v_pk_mul_f32 v[52:53], v[42:43], v[6:7] op_sel_hi:[0,1]
	v_pk_mul_f32 v[54:55], v[42:43], v[54:55] op_sel_hi:[0,1]
	s_waitcnt vmcnt(1)
	v_pk_mul_f32 v[4:5], v[4:5], v[8:9]
	v_pk_mul_f32 v[6:7], v[56:57], v[10:11]
	s_waitcnt vmcnt(0)
	v_pk_mul_f32 v[8:9], v[54:55], v[46:47]
	v_pk_mul_f32 v[10:11], v[52:53], v[48:49]
	global_store_dwordx4 v[50:51], v[4:7], off
	global_store_dwordx4 v[50:51], v[8:11], off offset:16
	global_load_dwordx4 v[4:7], v[34:35], off nt
	s_nop 0
	global_load_dwordx4 v[8:11], v[34:35], off offset:16 nt
	v_lshl_add_u64 v[46:47], s[10:11], 0, v[32:33]
	s_add_u32 s10, s10, s12
	v_lshlrev_b32_e32 v48, 16, v0
	v_and_b32_e32 v49, 0xffff0000, v0
	v_lshlrev_b32_e32 v0, 16, v1
	v_and_b32_e32 v1, 0xffff0000, v1
	s_addc_u32 s11, s11, s13
	v_lshlrev_b32_e32 v50, 16, v2
	v_and_b32_e32 v51, 0xffff0000, v2
	v_lshlrev_b32_e32 v2, 16, v3
	v_and_b32_e32 v3, 0xffff0000, v3
	v_pk_mul_f32 v[52:53], v[42:43], v[0:1] op_sel_hi:[0,1]
	v_pk_mul_f32 v[0:1], v[42:43], v[48:49] op_sel_hi:[0,1]
	s_cmpk_lt_i32 s0, 0x2000
	v_pk_mul_f32 v[48:49], v[42:43], v[2:3] op_sel_hi:[0,1]
	v_pk_mul_f32 v[50:51], v[42:43], v[50:51] op_sel_hi:[0,1]
	s_waitcnt vmcnt(1)
	v_pk_mul_f32 v[0:1], v[0:1], v[4:5]
	v_pk_mul_f32 v[2:3], v[52:53], v[6:7]
	s_waitcnt vmcnt(0)
	v_pk_mul_f32 v[4:5], v[50:51], v[8:9]
	v_pk_mul_f32 v[6:7], v[48:49], v[10:11]
	global_store_dwordx4 v[46:47], v[0:3], off
	global_store_dwordx4 v[46:47], v[4:7], off offset:16
	s_cbranch_scc1 .LBB0_4248
